# o3 plus: out-proj/down per-row sum-of-squares partials collected in LDS and written as one 16B store per row instead of 4B scattered stores
# speedup vs baseline: 1.0002x; 1.0002x over previous
; __device__ __forceinline__ u32x4 pack8(const f32x4 a, const f32x4 b) { u32x4 w; w.x = cvt_pk(a[0], a[1]); w.y = cvt_pk(a[2], a[3]); w.z = cvt_pk(b[0], b[1]); w.w = cvt_pk(b[2], b[3]); return w; }
; __device__ __forceinline__ f32x4 sigm4(f32x4 v) { f32x4 o; o[0] = sigm(v[0]); o[1] = sigm(v[1]); o[2] = sigm(v[2]); o[3] = sigm(v[3]); return o; }
; __device__ __forceinline__ float sq4(f32x4 v) { return (v[0] * v[0] + v[1] * v[1]) + (v[2] * v[2] + v[3] * v[3]); }
; #define EP_ROWLOOP for (int ai = 0; ai < 2; ++ai) _Pragma("unroll") for (int m = 0; m < 4; ++m)
;     __device__ __forceinline__ void operator()(const f32x4 (&acc)[2][2][4][2], const Unit& u, int wr, int wc, int fr, int fq) const {
;         const int rowb = u.pm * 256 + wr * 64 + fr, cb = u.pn * 256 + wc * 32 + 8 * fq;
; #pragma unroll
;         EP_ROWLOOP { EpFence fence_{(m & (EPB - 1)) == EPB - 1};
;             const int row = rowb + ai * 128 + m * 16;
;             float rs = 1.0f; if constexpr (MODE == 1) rs = rs_get<32>(rc, ssin, u.pm, wr * 64 + fr + ai * 128 + m * 16, fq, 1.0f / 2048.0f, 1e-6f);
;             float s = 0.f;
; #pragma unroll
;             for (int bj = 0; bj < 2; ++bj) {
;                 const size_t off = (size_t)row * 2048 + cb + bj * 128;
;                 f32x4 v0 = acc[ai][bj][m][0], v1 = acc[ai][bj][m][1], x0, x1;
;                 if constexpr (MODE == 1) { f32x4 e0, e1; unpack8(*(const u32x4*)(e + off), e0, e1); v0 = sigm4(v0 * rs) * e0; v1 = sigm4(v1 * rs) * e1; }
;                 unpack8(*(const u32x4*)(xold + off), x0, x1);
;                 v0 += x0; v1 += x1;
;                 *(u32x4*)(xnew + off) = pack8(v0, v1);
;                 s += sq4(v0) + sq4(v1);
;             }
;             s += __shfl_xor(s, 16); s += __shfl_xor(s, 32);
;             if (fq == 0) ssout[(size_t)row * 32 + u.pn * 4 + wc] = s;
.LBB0_255:
	v_lshrrev_b32_e32 v172, 6, v0
	v_lshrrev_b32_e32 v173, 2, v172
	v_and_b32_e32 v174, 3, v172
	v_and_b32_e32 v175, 15, v0
	v_lshl_add_u32 v168, v173, 6, v175
	v_lshlrev_b32_e32 v168, 4, v168
	v_lshl_add_u32 v168, v174, 2, v168
	v_add_u32_e32 v168, 0x20400, v168
	v_and_b32_e32 v144, 64, v190
	v_xor_b32_e32 v143, 16, v190
	v_add_u32_e32 v144, 64, v144
	v_cmp_lt_i32_e32 vcc, v143, v144
	v_lshl_add_u32 v142, s80, 8, v146
	v_lshl_or_b32 v140, s56, 8, v148
	v_cndmask_b32_e32 v143, v190, v143, vcc
	s_waitcnt vmcnt(0)
	v_lshlrev_b32_e32 v151, 2, v143
	v_xor_b32_e32 v143, 32, v190
	v_cmp_lt_i32_e32 vcc, v143, v144
	v_ashrrev_i32_e32 v141, 31, v140
	s_lshl_b32 s8, s56, 2
	v_cndmask_b32_e32 v143, v190, v143, vcc
	v_lshlrev_b32_e32 v150, 2, v143
	v_ashrrev_i32_e32 v143, 31, v142
	v_lshlrev_b64 v[144:145], 12, v[142:143]
	v_lshl_add_u64 v[144:145], s[26:27], 0, v[144:145]
	v_lshl_add_u64 v[144:145], v[140:141], 1, v[144:145]
	global_load_dwordx4 v[152:155], v[144:145], off
	s_ashr_i32 s9, s8, 31
	s_waitcnt vmcnt(0)
	v_lshlrev_b32_e32 v156, 16, v152
	v_and_b32_e32 v157, 0xffff0000, v152
	v_lshlrev_b32_e32 v152, 16, v153
	v_and_b32_e32 v153, 0xffff0000, v153
	v_lshlrev_b32_e32 v158, 16, v154
	v_and_b32_e32 v159, 0xffff0000, v154
	v_lshlrev_b32_e32 v154, 16, v155
	v_and_b32_e32 v155, 0xffff0000, v155
	v_pk_add_f32 v[152:153], v[124:125], v[152:153]
	v_pk_add_f32 v[156:157], v[122:123], v[156:157]
	v_pk_add_f32 v[128:129], v[128:129], v[154:155]
	v_pk_add_f32 v[126:127], v[126:127], v[158:159]
	v_cvt_pk_bf16_f32 v122, v156, v157
	v_cvt_pk_bf16_f32 v123, v152, v153
	v_cvt_pk_bf16_f32 v124, v126, v127
	v_cvt_pk_bf16_f32 v125, v128, v129
	global_store_dwordx4 v[144:145], v[122:125], off
	s_nop 1
	v_mul_f32_e32 v122, v157, v157
	v_mul_f32_e32 v123, v153, v153
	v_fmac_f32_e32 v122, v156, v156
	v_fmac_f32_e32 v123, v152, v152
	v_add_f32_e32 v122, v122, v123
	v_mul_f32_e32 v123, v127, v127
	v_mul_f32_e32 v124, v129, v129
	v_fmac_f32_e32 v123, v126, v126
	v_fmac_f32_e32 v124, v128, v128
	v_add_f32_e32 v123, v123, v124
	v_add_f32_e32 v152, v122, v123
	global_load_dwordx4 v[122:125], v[144:145], off offset:256
	s_waitcnt vmcnt(0)
	v_lshlrev_b32_e32 v126, 16, v122
	v_and_b32_e32 v127, 0xffff0000, v122
	v_lshlrev_b32_e32 v122, 16, v123
	v_and_b32_e32 v123, 0xffff0000, v123
	v_lshlrev_b32_e32 v128, 16, v124
	v_and_b32_e32 v129, 0xffff0000, v124
	v_lshlrev_b32_e32 v124, 16, v125
	v_and_b32_e32 v125, 0xffff0000, v125
	v_pk_add_f32 v[120:121], v[120:121], v[122:123]
	v_pk_add_f32 v[118:119], v[118:119], v[126:127]
	v_pk_add_f32 v[122:123], v[116:117], v[124:125]
	v_pk_add_f32 v[124:125], v[114:115], v[128:129]
	v_cvt_pk_bf16_f32 v114, v118, v119
	v_cvt_pk_bf16_f32 v115, v120, v121
	v_cvt_pk_bf16_f32 v116, v124, v125
	v_cvt_pk_bf16_f32 v117, v122, v123
	global_store_dwordx4 v[144:145], v[114:117], off offset:256
	s_nop 1
	v_mul_f32_e32 v114, v119, v119
	v_mul_f32_e32 v115, v121, v121
	v_fmac_f32_e32 v114, v118, v118
	v_fmac_f32_e32 v115, v120, v120
	v_add_f32_e32 v114, v114, v115
	v_mul_f32_e32 v115, v125, v125
	v_mul_f32_e32 v116, v123, v123
	v_fmac_f32_e32 v115, v124, v124
	v_fmac_f32_e32 v116, v122, v122
	v_add_f32_e32 v115, v115, v116
	v_add_f32_e32 v114, v114, v115
	v_add_f32_e32 v114, v152, v114
	ds_bpermute_b32 v115, v151, v114
	s_waitcnt lgkmcnt(0)
	v_add_f32_e32 v114, v114, v115
	ds_bpermute_b32 v115, v150, v114
	s_and_saveexec_b64 s[10:11], s[38:39]
	s_cbranch_execz .LBB0_257
	v_lshlrev_b64 v[116:117], 7, v[142:143]
	v_lshl_add_u64 v[116:117], s[28:29], 0, v[116:117]
	v_lshl_add_u64 v[116:117], s[8:9], 2, v[116:117]
	s_lshl_b32 s56, s51, 2
	v_lshl_add_u64 v[116:117], v[116:117], 0, s[56:57]
	s_waitcnt lgkmcnt(0)
	v_add_f32_e32 v114, v114, v115
	ds_write_b32 v168, v114
.LBB0_257:
	s_or_b64 exec, exec, s[10:11]
	v_or_b32_e32 v114, 16, v142
	s_waitcnt lgkmcnt(0)
	v_ashrrev_i32_e32 v115, 31, v114
	v_lshlrev_b64 v[116:117], 12, v[114:115]
	v_lshl_add_u64 v[116:117], s[26:27], 0, v[116:117]
	v_lshl_add_u64 v[120:121], v[140:141], 1, v[116:117]
	global_load_dwordx4 v[116:119], v[120:121], off
	s_waitcnt vmcnt(0)
	v_lshlrev_b32_e32 v122, 16, v116
	v_and_b32_e32 v123, 0xffff0000, v116
	v_lshlrev_b32_e32 v116, 16, v117
	v_and_b32_e32 v117, 0xffff0000, v117
	v_lshlrev_b32_e32 v124, 16, v118
	v_and_b32_e32 v125, 0xffff0000, v118
	v_lshlrev_b32_e32 v118, 16, v119
	v_and_b32_e32 v119, 0xffff0000, v119
	v_pk_add_f32 v[112:113], v[112:113], v[116:117]
	v_pk_add_f32 v[110:111], v[110:111], v[122:123]
	v_pk_add_f32 v[116:117], v[108:109], v[118:119]
	v_pk_add_f32 v[118:119], v[106:107], v[124:125]
	v_cvt_pk_bf16_f32 v106, v110, v111
	v_cvt_pk_bf16_f32 v107, v112, v113
	v_cvt_pk_bf16_f32 v108, v118, v119
	v_cvt_pk_bf16_f32 v109, v116, v117
	global_store_dwordx4 v[120:121], v[106:109], off
	s_nop 1
	v_mul_f32_e32 v106, v111, v111
	v_mul_f32_e32 v107, v113, v113
	v_fmac_f32_e32 v106, v110, v110
	v_fmac_f32_e32 v107, v112, v112
	v_add_f32_e32 v106, v106, v107
	v_mul_f32_e32 v107, v119, v119
	v_mul_f32_e32 v108, v117, v117
	v_fmac_f32_e32 v107, v118, v118
	v_fmac_f32_e32 v108, v116, v116
	v_add_f32_e32 v107, v107, v108
	v_add_f32_e32 v116, v106, v107
	global_load_dwordx4 v[106:109], v[120:121], off offset:256
	s_waitcnt vmcnt(0)
	v_lshlrev_b32_e32 v110, 16, v106
	v_and_b32_e32 v111, 0xffff0000, v106
	v_lshlrev_b32_e32 v106, 16, v107
	v_and_b32_e32 v107, 0xffff0000, v107
	v_lshlrev_b32_e32 v112, 16, v108
	v_and_b32_e32 v113, 0xffff0000, v108
	v_lshlrev_b32_e32 v108, 16, v109
	v_and_b32_e32 v109, 0xffff0000, v109
	v_pk_add_f32 v[104:105], v[104:105], v[106:107]
	v_pk_add_f32 v[102:103], v[102:103], v[110:111]
	v_pk_add_f32 v[106:107], v[100:101], v[108:109]
	v_pk_add_f32 v[108:109], v[98:99], v[112:113]
	v_cvt_pk_bf16_f32 v98, v102, v103
	v_cvt_pk_bf16_f32 v99, v104, v105
	v_cvt_pk_bf16_f32 v100, v108, v109
	v_cvt_pk_bf16_f32 v101, v106, v107
	global_store_dwordx4 v[120:121], v[98:101], off offset:256
	s_nop 1
	v_mul_f32_e32 v98, v103, v103
	v_mul_f32_e32 v99, v105, v105
	v_fmac_f32_e32 v98, v102, v102
	v_fmac_f32_e32 v99, v104, v104
	v_add_f32_e32 v98, v98, v99
	v_mul_f32_e32 v99, v109, v109
	v_mul_f32_e32 v100, v107, v107
	v_fmac_f32_e32 v99, v108, v108
	v_fmac_f32_e32 v100, v106, v106
	v_add_f32_e32 v99, v99, v100
	v_add_f32_e32 v98, v98, v99
	v_add_f32_e32 v98, v116, v98
	ds_bpermute_b32 v99, v151, v98
	s_waitcnt lgkmcnt(0)
	v_add_f32_e32 v98, v98, v99
	ds_bpermute_b32 v99, v150, v98
	s_and_saveexec_b64 s[10:11], s[38:39]
	s_cbranch_execz .LBB0_259
	v_lshlrev_b64 v[100:101], 7, v[114:115]
	v_lshl_add_u64 v[100:101], s[28:29], 0, v[100:101]
	v_lshl_add_u64 v[100:101], s[8:9], 2, v[100:101]
	s_lshl_b32 s56, s51, 2
	v_lshl_add_u64 v[100:101], v[100:101], 0, s[56:57]
	s_waitcnt lgkmcnt(0)
	v_add_f32_e32 v98, v98, v99
	ds_write_b32 v168, v98 offset:256
; __device__ __forceinline__ u32x4 pack8(const f32x4 a, const f32x4 b) { u32x4 w; w.x = cvt_pk(a[0], a[1]); w.y = cvt_pk(a[2], a[3]); w.z = cvt_pk(b[0], b[1]); w.w = cvt_pk(b[2], b[3]); return w; }
; __device__ __forceinline__ f32x4 sigm4(f32x4 v) { f32x4 o; o[0] = sigm(v[0]); o[1] = sigm(v[1]); o[2] = sigm(v[2]); o[3] = sigm(v[3]); return o; }
; __device__ __forceinline__ float sq4(f32x4 v) { return (v[0] * v[0] + v[1] * v[1]) + (v[2] * v[2] + v[3] * v[3]); }
; #define EP_ROWLOOP for (int ai = 0; ai < 2; ++ai) _Pragma("unroll") for (int m = 0; m < 4; ++m)
;     __device__ __forceinline__ void operator()(const f32x4 (&acc)[2][2][4][2], const Unit& u, int wr, int wc, int fr, int fq) const {
;         const int rowb = u.pm * 256 + wr * 64 + fr, cb = u.pn * 256 + wc * 32 + 8 * fq;
; #pragma unroll
;         EP_ROWLOOP { EpFence fence_{(m & (EPB - 1)) == EPB - 1};
;             const int row = rowb + ai * 128 + m * 16;
;             float rs = 1.0f; if constexpr (MODE == 1) rs = rs_get<32>(rc, ssin, u.pm, wr * 64 + fr + ai * 128 + m * 16, fq, 1.0f / 2048.0f, 1e-6f);
;             float s = 0.f;
; #pragma unroll
;             for (int bj = 0; bj < 2; ++bj) {
;                 const size_t off = (size_t)row * 2048 + cb + bj * 128;
;                 f32x4 v0 = acc[ai][bj][m][0], v1 = acc[ai][bj][m][1], x0, x1;
;                 if constexpr (MODE == 1) { f32x4 e0, e1; unpack8(*(const u32x4*)(e + off), e0, e1); v0 = sigm4(v0 * rs) * e0; v1 = sigm4(v1 * rs) * e1; }
;                 unpack8(*(const u32x4*)(xold + off), x0, x1);
;                 v0 += x0; v1 += x1;
;                 *(u32x4*)(xnew + off) = pack8(v0, v1);
;                 s += sq4(v0) + sq4(v1);
;             }
;             s += __shfl_xor(s, 16); s += __shfl_xor(s, 32);
;             if (fq == 0) ssout[(size_t)row * 32 + u.pn * 4 + wc] = s;
.LBB0_259:
	s_or_b64 exec, exec, s[10:11]
	v_or_b32_e32 v98, 32, v142
	s_waitcnt lgkmcnt(0)
	v_ashrrev_i32_e32 v99, 31, v98
	v_lshlrev_b64 v[100:101], 12, v[98:99]
	v_lshl_add_u64 v[100:101], s[26:27], 0, v[100:101]
	v_lshl_add_u64 v[104:105], v[140:141], 1, v[100:101]
	global_load_dwordx4 v[100:103], v[104:105], off
	s_waitcnt vmcnt(0)
	v_lshlrev_b32_e32 v106, 16, v100
	v_and_b32_e32 v107, 0xffff0000, v100
	v_lshlrev_b32_e32 v100, 16, v101
	v_and_b32_e32 v101, 0xffff0000, v101
	v_lshlrev_b32_e32 v108, 16, v102
	v_and_b32_e32 v109, 0xffff0000, v102
	v_lshlrev_b32_e32 v102, 16, v103
	v_and_b32_e32 v103, 0xffff0000, v103
	v_pk_add_f32 v[96:97], v[96:97], v[100:101]
	v_pk_add_f32 v[94:95], v[94:95], v[106:107]
	v_pk_add_f32 v[100:101], v[92:93], v[102:103]
	v_pk_add_f32 v[102:103], v[90:91], v[108:109]
	v_cvt_pk_bf16_f32 v90, v94, v95
	v_cvt_pk_bf16_f32 v91, v96, v97
	v_cvt_pk_bf16_f32 v92, v102, v103
	v_cvt_pk_bf16_f32 v93, v100, v101
	global_store_dwordx4 v[104:105], v[90:93], off
	s_nop 1
	v_mul_f32_e32 v90, v95, v95
	v_mul_f32_e32 v91, v97, v97
	v_fmac_f32_e32 v90, v94, v94
	v_fmac_f32_e32 v91, v96, v96
	v_add_f32_e32 v90, v90, v91
	v_mul_f32_e32 v91, v103, v103
	v_mul_f32_e32 v92, v101, v101
	v_fmac_f32_e32 v91, v102, v102
	v_fmac_f32_e32 v92, v100, v100
	v_add_f32_e32 v91, v91, v92
	v_add_f32_e32 v100, v90, v91
	global_load_dwordx4 v[90:93], v[104:105], off offset:256
	s_waitcnt vmcnt(0)
	v_lshlrev_b32_e32 v94, 16, v90
	v_and_b32_e32 v95, 0xffff0000, v90
	v_lshlrev_b32_e32 v90, 16, v91
	v_and_b32_e32 v91, 0xffff0000, v91
	v_lshlrev_b32_e32 v96, 16, v92
	v_and_b32_e32 v97, 0xffff0000, v92
	v_lshlrev_b32_e32 v92, 16, v93
	v_and_b32_e32 v93, 0xffff0000, v93
	v_pk_add_f32 v[88:89], v[88:89], v[90:91]
	v_pk_add_f32 v[86:87], v[86:87], v[94:95]
	v_pk_add_f32 v[90:91], v[84:85], v[92:93]
	v_pk_add_f32 v[92:93], v[82:83], v[96:97]
	v_cvt_pk_bf16_f32 v82, v86, v87
	v_cvt_pk_bf16_f32 v83, v88, v89
	v_cvt_pk_bf16_f32 v84, v92, v93
	v_cvt_pk_bf16_f32 v85, v90, v91
	global_store_dwordx4 v[104:105], v[82:85], off offset:256
	s_nop 1
	v_mul_f32_e32 v82, v87, v87
	v_mul_f32_e32 v83, v89, v89
	v_fmac_f32_e32 v82, v86, v86
	v_fmac_f32_e32 v83, v88, v88
	v_add_f32_e32 v82, v82, v83
	v_mul_f32_e32 v83, v93, v93
	v_mul_f32_e32 v84, v91, v91
	v_fmac_f32_e32 v83, v92, v92
	v_fmac_f32_e32 v84, v90, v90
	v_add_f32_e32 v83, v83, v84
	v_add_f32_e32 v82, v82, v83
	v_add_f32_e32 v82, v100, v82
	ds_bpermute_b32 v83, v151, v82
	s_waitcnt lgkmcnt(0)
	v_add_f32_e32 v82, v82, v83
	ds_bpermute_b32 v83, v150, v82
	s_and_saveexec_b64 s[10:11], s[38:39]
	s_cbranch_execz .LBB0_261
	v_lshlrev_b64 v[84:85], 7, v[98:99]
	v_lshl_add_u64 v[84:85], s[28:29], 0, v[84:85]
	v_lshl_add_u64 v[84:85], s[8:9], 2, v[84:85]
	s_lshl_b32 s56, s51, 2
	v_lshl_add_u64 v[84:85], v[84:85], 0, s[56:57]
	s_waitcnt lgkmcnt(0)
	v_add_f32_e32 v82, v82, v83
	ds_write_b32 v168, v82 offset:512
.LBB0_261:
	s_or_b64 exec, exec, s[10:11]
	v_or_b32_e32 v82, 48, v142
	s_waitcnt lgkmcnt(0)
	v_ashrrev_i32_e32 v83, 31, v82
	v_lshlrev_b64 v[84:85], 12, v[82:83]
	v_lshl_add_u64 v[84:85], s[26:27], 0, v[84:85]
	v_lshl_add_u64 v[88:89], v[140:141], 1, v[84:85]
	global_load_dwordx4 v[84:87], v[88:89], off
	s_waitcnt vmcnt(0)
	v_lshlrev_b32_e32 v90, 16, v84
	v_and_b32_e32 v91, 0xffff0000, v84
	v_lshlrev_b32_e32 v84, 16, v85
	v_and_b32_e32 v85, 0xffff0000, v85
	v_lshlrev_b32_e32 v92, 16, v86
	v_and_b32_e32 v93, 0xffff0000, v86
	v_lshlrev_b32_e32 v86, 16, v87
	v_and_b32_e32 v87, 0xffff0000, v87
	v_pk_add_f32 v[80:81], v[80:81], v[84:85]
	v_pk_add_f32 v[78:79], v[78:79], v[90:91]
	v_pk_add_f32 v[84:85], v[76:77], v[86:87]
	v_pk_add_f32 v[86:87], v[74:75], v[92:93]
	v_cvt_pk_bf16_f32 v74, v78, v79
	v_cvt_pk_bf16_f32 v75, v80, v81
	v_cvt_pk_bf16_f32 v76, v86, v87
	v_cvt_pk_bf16_f32 v77, v84, v85
	global_store_dwordx4 v[88:89], v[74:77], off
	s_nop 1
	v_mul_f32_e32 v74, v79, v79
	v_mul_f32_e32 v75, v81, v81
	v_fmac_f32_e32 v74, v78, v78
	v_fmac_f32_e32 v75, v80, v80
	v_add_f32_e32 v74, v74, v75
	v_mul_f32_e32 v75, v87, v87
	v_mul_f32_e32 v76, v85, v85
	v_fmac_f32_e32 v75, v86, v86
	v_fmac_f32_e32 v76, v84, v84
	v_add_f32_e32 v75, v75, v76
	v_add_f32_e32 v84, v74, v75
	global_load_dwordx4 v[74:77], v[88:89], off offset:256
	s_waitcnt vmcnt(0)
	v_lshlrev_b32_e32 v78, 16, v74
	v_and_b32_e32 v79, 0xffff0000, v74
	v_lshlrev_b32_e32 v74, 16, v75
	v_and_b32_e32 v75, 0xffff0000, v75
	v_lshlrev_b32_e32 v80, 16, v76
	v_and_b32_e32 v81, 0xffff0000, v76
	v_lshlrev_b32_e32 v76, 16, v77
	v_and_b32_e32 v77, 0xffff0000, v77
	v_pk_add_f32 v[72:73], v[72:73], v[74:75]
	v_pk_add_f32 v[70:71], v[70:71], v[78:79]
	v_pk_add_f32 v[74:75], v[68:69], v[76:77]
	v_pk_add_f32 v[76:77], v[66:67], v[80:81]
	v_cvt_pk_bf16_f32 v66, v70, v71
	v_cvt_pk_bf16_f32 v67, v72, v73
	v_cvt_pk_bf16_f32 v68, v76, v77
	v_cvt_pk_bf16_f32 v69, v74, v75
	global_store_dwordx4 v[88:89], v[66:69], off offset:256
	s_nop 1
	v_mul_f32_e32 v66, v71, v71
	v_mul_f32_e32 v67, v73, v73
	v_fmac_f32_e32 v66, v70, v70
	v_fmac_f32_e32 v67, v72, v72
	v_add_f32_e32 v66, v66, v67
	v_mul_f32_e32 v67, v77, v77
	v_mul_f32_e32 v68, v75, v75
	v_fmac_f32_e32 v67, v76, v76
	v_fmac_f32_e32 v68, v74, v74
	v_add_f32_e32 v67, v67, v68
	v_add_f32_e32 v66, v66, v67
	v_add_f32_e32 v66, v84, v66
	ds_bpermute_b32 v67, v151, v66
	s_waitcnt lgkmcnt(0)
	v_add_f32_e32 v66, v66, v67
	ds_bpermute_b32 v67, v150, v66
	s_and_saveexec_b64 s[10:11], s[38:39]
	s_cbranch_execz .LBB0_263
	v_lshlrev_b64 v[68:69], 7, v[82:83]
	v_lshl_add_u64 v[68:69], s[28:29], 0, v[68:69]
	v_lshl_add_u64 v[68:69], s[8:9], 2, v[68:69]
	s_lshl_b32 s56, s51, 2
	v_lshl_add_u64 v[68:69], v[68:69], 0, s[56:57]
	s_waitcnt lgkmcnt(0)
	v_add_f32_e32 v66, v66, v67
	ds_write_b32 v168, v66 offset:768
; __device__ __forceinline__ u32x4 pack8(const f32x4 a, const f32x4 b) { u32x4 w; w.x = cvt_pk(a[0], a[1]); w.y = cvt_pk(a[2], a[3]); w.z = cvt_pk(b[0], b[1]); w.w = cvt_pk(b[2], b[3]); return w; }
; __device__ __forceinline__ f32x4 sigm4(f32x4 v) { f32x4 o; o[0] = sigm(v[0]); o[1] = sigm(v[1]); o[2] = sigm(v[2]); o[3] = sigm(v[3]); return o; }
; __device__ __forceinline__ float sq4(f32x4 v) { return (v[0] * v[0] + v[1] * v[1]) + (v[2] * v[2] + v[3] * v[3]); }
; #define EP_ROWLOOP for (int ai = 0; ai < 2; ++ai) _Pragma("unroll") for (int m = 0; m < 4; ++m)
;     __device__ __forceinline__ void operator()(const f32x4 (&acc)[2][2][4][2], const Unit& u, int wr, int wc, int fr, int fq) const {
;         const int rowb = u.pm * 256 + wr * 64 + fr, cb = u.pn * 256 + wc * 32 + 8 * fq;
; #pragma unroll
;         EP_ROWLOOP { EpFence fence_{(m & (EPB - 1)) == EPB - 1};
;             const int row = rowb + ai * 128 + m * 16;
;             float rs = 1.0f; if constexpr (MODE == 1) rs = rs_get<32>(rc, ssin, u.pm, wr * 64 + fr + ai * 128 + m * 16, fq, 1.0f / 2048.0f, 1e-6f);
;             float s = 0.f;
; #pragma unroll
;             for (int bj = 0; bj < 2; ++bj) {
;                 const size_t off = (size_t)row * 2048 + cb + bj * 128;
;                 f32x4 v0 = acc[ai][bj][m][0], v1 = acc[ai][bj][m][1], x0, x1;
;                 if constexpr (MODE == 1) { f32x4 e0, e1; unpack8(*(const u32x4*)(e + off), e0, e1); v0 = sigm4(v0 * rs) * e0; v1 = sigm4(v1 * rs) * e1; }
;                 unpack8(*(const u32x4*)(xold + off), x0, x1);
;                 v0 += x0; v1 += x1;
;                 *(u32x4*)(xnew + off) = pack8(v0, v1);
;                 s += sq4(v0) + sq4(v1);
;             }
;             s += __shfl_xor(s, 16); s += __shfl_xor(s, 32);
;             if (fq == 0) ssout[(size_t)row * 32 + u.pn * 4 + wc] = s;
.LBB0_263:
	s_or_b64 exec, exec, s[10:11]
	v_add_u32_e32 v66, 0x80, v142
	s_waitcnt lgkmcnt(0)
	v_ashrrev_i32_e32 v67, 31, v66
	v_lshlrev_b64 v[68:69], 12, v[66:67]
	v_lshl_add_u64 v[68:69], s[26:27], 0, v[68:69]
	v_lshl_add_u64 v[72:73], v[140:141], 1, v[68:69]
	global_load_dwordx4 v[68:71], v[72:73], off
	s_waitcnt vmcnt(0)
	v_lshlrev_b32_e32 v74, 16, v68
	v_and_b32_e32 v75, 0xffff0000, v68
	v_lshlrev_b32_e32 v68, 16, v69
	v_and_b32_e32 v69, 0xffff0000, v69
	v_lshlrev_b32_e32 v76, 16, v70
	v_and_b32_e32 v77, 0xffff0000, v70
	v_lshlrev_b32_e32 v70, 16, v71
	v_and_b32_e32 v71, 0xffff0000, v71
	v_pk_add_f32 v[64:65], v[64:65], v[68:69]
	v_pk_add_f32 v[62:63], v[62:63], v[74:75]
	v_pk_add_f32 v[68:69], v[60:61], v[70:71]
	v_pk_add_f32 v[70:71], v[58:59], v[76:77]
	v_cvt_pk_bf16_f32 v58, v62, v63
	v_cvt_pk_bf16_f32 v59, v64, v65
	v_cvt_pk_bf16_f32 v60, v70, v71
	v_cvt_pk_bf16_f32 v61, v68, v69
	global_store_dwordx4 v[72:73], v[58:61], off
	s_nop 1
	v_mul_f32_e32 v58, v63, v63
	v_mul_f32_e32 v59, v65, v65
	v_fmac_f32_e32 v58, v62, v62
	v_fmac_f32_e32 v59, v64, v64
	v_add_f32_e32 v58, v58, v59
	v_mul_f32_e32 v59, v71, v71
	v_mul_f32_e32 v60, v69, v69
	v_fmac_f32_e32 v59, v70, v70
	v_fmac_f32_e32 v60, v68, v68
	v_add_f32_e32 v59, v59, v60
	v_add_f32_e32 v68, v58, v59
	global_load_dwordx4 v[58:61], v[72:73], off offset:256
	s_waitcnt vmcnt(0)
	v_lshlrev_b32_e32 v62, 16, v58
	v_and_b32_e32 v63, 0xffff0000, v58
	v_lshlrev_b32_e32 v58, 16, v59
	v_and_b32_e32 v59, 0xffff0000, v59
	v_lshlrev_b32_e32 v64, 16, v60
	v_and_b32_e32 v65, 0xffff0000, v60
	v_lshlrev_b32_e32 v60, 16, v61
	v_and_b32_e32 v61, 0xffff0000, v61
	v_pk_add_f32 v[56:57], v[56:57], v[58:59]
	v_pk_add_f32 v[54:55], v[54:55], v[62:63]
	v_pk_add_f32 v[58:59], v[52:53], v[60:61]
	v_pk_add_f32 v[60:61], v[50:51], v[64:65]
	v_cvt_pk_bf16_f32 v50, v54, v55
	v_cvt_pk_bf16_f32 v51, v56, v57
	v_cvt_pk_bf16_f32 v52, v60, v61
	v_cvt_pk_bf16_f32 v53, v58, v59
	global_store_dwordx4 v[72:73], v[50:53], off offset:256
	s_nop 1
	v_mul_f32_e32 v50, v55, v55
	v_mul_f32_e32 v51, v57, v57
	v_fmac_f32_e32 v50, v54, v54
	v_fmac_f32_e32 v51, v56, v56
	v_add_f32_e32 v50, v50, v51
	v_mul_f32_e32 v51, v61, v61
	v_mul_f32_e32 v52, v59, v59
	v_fmac_f32_e32 v51, v60, v60
	v_fmac_f32_e32 v52, v58, v58
	v_add_f32_e32 v51, v51, v52
	v_add_f32_e32 v50, v50, v51
	v_add_f32_e32 v50, v68, v50
	ds_bpermute_b32 v51, v151, v50
	s_waitcnt lgkmcnt(0)
	v_add_f32_e32 v50, v50, v51
	ds_bpermute_b32 v51, v150, v50
	s_and_saveexec_b64 s[10:11], s[38:39]
	s_cbranch_execz .LBB0_265
	v_lshlrev_b64 v[52:53], 7, v[66:67]
	v_lshl_add_u64 v[52:53], s[28:29], 0, v[52:53]
	v_lshl_add_u64 v[52:53], s[8:9], 2, v[52:53]
	s_lshl_b32 s56, s51, 2
	v_lshl_add_u64 v[52:53], v[52:53], 0, s[56:57]
	s_waitcnt lgkmcnt(0)
	v_add_f32_e32 v50, v50, v51
	ds_write_b32 v168, v50 offset:2048
.LBB0_265:
	s_or_b64 exec, exec, s[10:11]
	v_add_u32_e32 v50, 0x90, v142
	s_waitcnt lgkmcnt(0)
	v_ashrrev_i32_e32 v51, 31, v50
	v_lshlrev_b64 v[52:53], 12, v[50:51]
	v_lshl_add_u64 v[52:53], s[26:27], 0, v[52:53]
	v_lshl_add_u64 v[56:57], v[140:141], 1, v[52:53]
	global_load_dwordx4 v[52:55], v[56:57], off
	s_waitcnt vmcnt(0)
	v_lshlrev_b32_e32 v58, 16, v52
	v_and_b32_e32 v59, 0xffff0000, v52
	v_lshlrev_b32_e32 v52, 16, v53
	v_and_b32_e32 v53, 0xffff0000, v53
	v_lshlrev_b32_e32 v60, 16, v54
	v_and_b32_e32 v61, 0xffff0000, v54
	v_lshlrev_b32_e32 v54, 16, v55
	v_and_b32_e32 v55, 0xffff0000, v55
	v_pk_add_f32 v[48:49], v[48:49], v[52:53]
	v_pk_add_f32 v[46:47], v[46:47], v[58:59]
	v_pk_add_f32 v[52:53], v[44:45], v[54:55]
	v_pk_add_f32 v[54:55], v[42:43], v[60:61]
	v_cvt_pk_bf16_f32 v42, v46, v47
	v_cvt_pk_bf16_f32 v43, v48, v49
	v_cvt_pk_bf16_f32 v44, v54, v55
	v_cvt_pk_bf16_f32 v45, v52, v53
	global_store_dwordx4 v[56:57], v[42:45], off
	s_nop 1
	v_mul_f32_e32 v42, v47, v47
	v_mul_f32_e32 v43, v49, v49
	v_fmac_f32_e32 v42, v46, v46
	v_fmac_f32_e32 v43, v48, v48
	v_add_f32_e32 v42, v42, v43
	v_mul_f32_e32 v43, v55, v55
	v_mul_f32_e32 v44, v53, v53
	v_fmac_f32_e32 v43, v54, v54
	v_fmac_f32_e32 v44, v52, v52
	v_add_f32_e32 v43, v43, v44
	v_add_f32_e32 v52, v42, v43
	global_load_dwordx4 v[42:45], v[56:57], off offset:256
	s_waitcnt vmcnt(0)
	v_lshlrev_b32_e32 v46, 16, v42
	v_and_b32_e32 v47, 0xffff0000, v42
	v_lshlrev_b32_e32 v42, 16, v43
	v_and_b32_e32 v43, 0xffff0000, v43
	v_lshlrev_b32_e32 v48, 16, v44
	v_and_b32_e32 v49, 0xffff0000, v44
	v_lshlrev_b32_e32 v44, 16, v45
	v_and_b32_e32 v45, 0xffff0000, v45
	v_pk_add_f32 v[40:41], v[40:41], v[42:43]
	v_pk_add_f32 v[38:39], v[38:39], v[46:47]
	v_pk_add_f32 v[42:43], v[36:37], v[44:45]
	v_pk_add_f32 v[44:45], v[34:35], v[48:49]
	v_cvt_pk_bf16_f32 v34, v38, v39
	v_cvt_pk_bf16_f32 v35, v40, v41
	v_cvt_pk_bf16_f32 v36, v44, v45
	v_cvt_pk_bf16_f32 v37, v42, v43
	global_store_dwordx4 v[56:57], v[34:37], off offset:256
	s_nop 1
	v_mul_f32_e32 v34, v39, v39
	v_mul_f32_e32 v35, v41, v41
	v_fmac_f32_e32 v34, v38, v38
	v_fmac_f32_e32 v35, v40, v40
	v_add_f32_e32 v34, v34, v35
	v_mul_f32_e32 v35, v45, v45
	v_mul_f32_e32 v36, v43, v43
	v_fmac_f32_e32 v35, v44, v44
	v_fmac_f32_e32 v36, v42, v42
	v_add_f32_e32 v35, v35, v36
	v_add_f32_e32 v34, v34, v35
	v_add_f32_e32 v34, v52, v34
	ds_bpermute_b32 v35, v151, v34
	s_waitcnt lgkmcnt(0)
	v_add_f32_e32 v34, v34, v35
	ds_bpermute_b32 v35, v150, v34
	s_and_saveexec_b64 s[10:11], s[38:39]
	s_cbranch_execz .LBB0_267
	v_lshlrev_b64 v[36:37], 7, v[50:51]
	v_lshl_add_u64 v[36:37], s[28:29], 0, v[36:37]
	v_lshl_add_u64 v[36:37], s[8:9], 2, v[36:37]
	s_lshl_b32 s56, s51, 2
	v_lshl_add_u64 v[36:37], v[36:37], 0, s[56:57]
	s_waitcnt lgkmcnt(0)
	v_add_f32_e32 v34, v34, v35
	ds_write_b32 v168, v34 offset:2304
; __device__ __forceinline__ u32x4 pack8(const f32x4 a, const f32x4 b) { u32x4 w; w.x = cvt_pk(a[0], a[1]); w.y = cvt_pk(a[2], a[3]); w.z = cvt_pk(b[0], b[1]); w.w = cvt_pk(b[2], b[3]); return w; }
; __device__ __forceinline__ f32x4 sigm4(f32x4 v) { f32x4 o; o[0] = sigm(v[0]); o[1] = sigm(v[1]); o[2] = sigm(v[2]); o[3] = sigm(v[3]); return o; }
; __device__ __forceinline__ float sq4(f32x4 v) { return (v[0] * v[0] + v[1] * v[1]) + (v[2] * v[2] + v[3] * v[3]); }
; #define EP_ROWLOOP for (int ai = 0; ai < 2; ++ai) _Pragma("unroll") for (int m = 0; m < 4; ++m)
;     __device__ __forceinline__ void operator()(const f32x4 (&acc)[2][2][4][2], const Unit& u, int wr, int wc, int fr, int fq) const {
;         const int rowb = u.pm * 256 + wr * 64 + fr, cb = u.pn * 256 + wc * 32 + 8 * fq;
; #pragma unroll
;         EP_ROWLOOP { EpFence fence_{(m & (EPB - 1)) == EPB - 1};
;             const int row = rowb + ai * 128 + m * 16;
;             float rs = 1.0f; if constexpr (MODE == 1) rs = rs_get<32>(rc, ssin, u.pm, wr * 64 + fr + ai * 128 + m * 16, fq, 1.0f / 2048.0f, 1e-6f);
;             float s = 0.f;
; #pragma unroll
;             for (int bj = 0; bj < 2; ++bj) {
;                 const size_t off = (size_t)row * 2048 + cb + bj * 128;
;                 f32x4 v0 = acc[ai][bj][m][0], v1 = acc[ai][bj][m][1], x0, x1;
;                 if constexpr (MODE == 1) { f32x4 e0, e1; unpack8(*(const u32x4*)(e + off), e0, e1); v0 = sigm4(v0 * rs) * e0; v1 = sigm4(v1 * rs) * e1; }
;                 unpack8(*(const u32x4*)(xold + off), x0, x1);
;                 v0 += x0; v1 += x1;
;                 *(u32x4*)(xnew + off) = pack8(v0, v1);
;                 s += sq4(v0) + sq4(v1);
;             }
;             s += __shfl_xor(s, 16); s += __shfl_xor(s, 32);
;             if (fq == 0) ssout[(size_t)row * 32 + u.pn * 4 + wc] = s;
.LBB0_267:
	s_or_b64 exec, exec, s[10:11]
	v_add_u32_e32 v34, 0xa0, v142
	s_waitcnt lgkmcnt(0)
	v_ashrrev_i32_e32 v35, 31, v34
	v_lshlrev_b64 v[36:37], 12, v[34:35]
	v_lshl_add_u64 v[36:37], s[26:27], 0, v[36:37]
	v_lshl_add_u64 v[40:41], v[140:141], 1, v[36:37]
	global_load_dwordx4 v[36:39], v[40:41], off
	s_waitcnt vmcnt(0)
	v_lshlrev_b32_e32 v42, 16, v36
	v_and_b32_e32 v43, 0xffff0000, v36
	v_lshlrev_b32_e32 v36, 16, v37
	v_and_b32_e32 v37, 0xffff0000, v37
	v_lshlrev_b32_e32 v44, 16, v38
	v_and_b32_e32 v45, 0xffff0000, v38
	v_lshlrev_b32_e32 v38, 16, v39
	v_and_b32_e32 v39, 0xffff0000, v39
	v_pk_add_f32 v[32:33], v[32:33], v[36:37]
	v_pk_add_f32 v[30:31], v[30:31], v[42:43]
	v_pk_add_f32 v[36:37], v[28:29], v[38:39]
	v_pk_add_f32 v[38:39], v[26:27], v[44:45]
	v_cvt_pk_bf16_f32 v26, v30, v31
	v_cvt_pk_bf16_f32 v27, v32, v33
	v_cvt_pk_bf16_f32 v28, v38, v39
	v_cvt_pk_bf16_f32 v29, v36, v37
	global_store_dwordx4 v[40:41], v[26:29], off
	s_nop 1
	v_mul_f32_e32 v26, v31, v31
	v_mul_f32_e32 v27, v33, v33
	v_fmac_f32_e32 v26, v30, v30
	v_fmac_f32_e32 v27, v32, v32
	v_add_f32_e32 v26, v26, v27
	v_mul_f32_e32 v27, v39, v39
	v_mul_f32_e32 v28, v37, v37
	v_fmac_f32_e32 v27, v38, v38
	v_fmac_f32_e32 v28, v36, v36
	v_add_f32_e32 v27, v27, v28
	v_add_f32_e32 v36, v26, v27
	global_load_dwordx4 v[26:29], v[40:41], off offset:256
	s_waitcnt vmcnt(0)
	v_lshlrev_b32_e32 v30, 16, v26
	v_and_b32_e32 v31, 0xffff0000, v26
	v_lshlrev_b32_e32 v26, 16, v27
	v_and_b32_e32 v27, 0xffff0000, v27
	v_lshlrev_b32_e32 v32, 16, v28
	v_and_b32_e32 v33, 0xffff0000, v28
	v_lshlrev_b32_e32 v28, 16, v29
	v_and_b32_e32 v29, 0xffff0000, v29
	v_pk_add_f32 v[24:25], v[24:25], v[26:27]
	v_pk_add_f32 v[22:23], v[22:23], v[30:31]
	v_pk_add_f32 v[26:27], v[20:21], v[28:29]
	v_pk_add_f32 v[28:29], v[18:19], v[32:33]
	v_cvt_pk_bf16_f32 v18, v22, v23
	v_cvt_pk_bf16_f32 v19, v24, v25
	v_cvt_pk_bf16_f32 v20, v28, v29
	v_cvt_pk_bf16_f32 v21, v26, v27
	global_store_dwordx4 v[40:41], v[18:21], off offset:256
	s_nop 1
	v_mul_f32_e32 v18, v23, v23
	v_mul_f32_e32 v19, v25, v25
	v_fmac_f32_e32 v18, v22, v22
	v_fmac_f32_e32 v19, v24, v24
	v_add_f32_e32 v18, v18, v19
	v_mul_f32_e32 v19, v29, v29
	v_mul_f32_e32 v20, v27, v27
	v_fmac_f32_e32 v19, v28, v28
	v_fmac_f32_e32 v20, v26, v26
	v_add_f32_e32 v19, v19, v20
	v_add_f32_e32 v18, v18, v19
	v_add_f32_e32 v18, v36, v18
	ds_bpermute_b32 v19, v151, v18
	s_waitcnt lgkmcnt(0)
	v_add_f32_e32 v18, v18, v19
	ds_bpermute_b32 v19, v150, v18
	s_and_saveexec_b64 s[10:11], s[38:39]
	s_cbranch_execz .LBB0_269
	v_lshlrev_b64 v[20:21], 7, v[34:35]
	v_lshl_add_u64 v[20:21], s[28:29], 0, v[20:21]
	v_lshl_add_u64 v[20:21], s[8:9], 2, v[20:21]
	s_lshl_b32 s56, s51, 2
	v_lshl_add_u64 v[20:21], v[20:21], 0, s[56:57]
	s_waitcnt lgkmcnt(0)
	v_add_f32_e32 v18, v18, v19
	ds_write_b32 v168, v18 offset:2560
.LBB0_269:
	s_or_b64 exec, exec, s[10:11]
	v_add_u32_e32 v18, 0xb0, v142
	s_waitcnt lgkmcnt(0)
	v_ashrrev_i32_e32 v19, 31, v18
	v_lshlrev_b64 v[20:21], 12, v[18:19]
	v_lshl_add_u64 v[20:21], s[26:27], 0, v[20:21]
	v_lshl_add_u64 v[24:25], v[140:141], 1, v[20:21]
	global_load_dwordx4 v[20:23], v[24:25], off
	s_waitcnt vmcnt(0)
	v_lshlrev_b32_e32 v26, 16, v20
	v_and_b32_e32 v27, 0xffff0000, v20
	v_lshlrev_b32_e32 v20, 16, v21
	v_and_b32_e32 v21, 0xffff0000, v21
	v_lshlrev_b32_e32 v28, 16, v22
	v_and_b32_e32 v29, 0xffff0000, v22
	v_lshlrev_b32_e32 v22, 16, v23
	v_and_b32_e32 v23, 0xffff0000, v23
	v_pk_add_f32 v[16:17], v[16:17], v[20:21]
	v_pk_add_f32 v[14:15], v[14:15], v[26:27]
	v_pk_add_f32 v[20:21], v[12:13], v[22:23]
	v_pk_add_f32 v[22:23], v[10:11], v[28:29]
	v_cvt_pk_bf16_f32 v10, v14, v15
	v_cvt_pk_bf16_f32 v11, v16, v17
	v_cvt_pk_bf16_f32 v12, v22, v23
	v_cvt_pk_bf16_f32 v13, v20, v21
	global_store_dwordx4 v[24:25], v[10:13], off
	s_nop 1
	v_mul_f32_e32 v10, v15, v15
	v_mul_f32_e32 v11, v17, v17
	v_fmac_f32_e32 v10, v14, v14
	v_fmac_f32_e32 v11, v16, v16
	v_add_f32_e32 v10, v10, v11
	v_mul_f32_e32 v11, v23, v23
	v_mul_f32_e32 v12, v21, v21
	v_fmac_f32_e32 v11, v22, v22
	v_fmac_f32_e32 v12, v20, v20
	v_add_f32_e32 v11, v11, v12
	v_add_f32_e32 v20, v10, v11
	global_load_dwordx4 v[10:13], v[24:25], off offset:256
	s_waitcnt vmcnt(0)
	v_lshlrev_b32_e32 v14, 16, v10
	v_and_b32_e32 v15, 0xffff0000, v10
	v_lshlrev_b32_e32 v10, 16, v11
	v_and_b32_e32 v11, 0xffff0000, v11
	v_lshlrev_b32_e32 v16, 16, v12
	v_and_b32_e32 v17, 0xffff0000, v12
	v_lshlrev_b32_e32 v12, 16, v13
	v_and_b32_e32 v13, 0xffff0000, v13
	v_pk_add_f32 v[8:9], v[8:9], v[10:11]
	v_pk_add_f32 v[6:7], v[6:7], v[14:15]
	v_pk_add_f32 v[10:11], v[4:5], v[12:13]
	v_pk_add_f32 v[12:13], v[2:3], v[16:17]
	v_cvt_pk_bf16_f32 v2, v6, v7
	v_cvt_pk_bf16_f32 v3, v8, v9
	v_cvt_pk_bf16_f32 v4, v12, v13
	v_cvt_pk_bf16_f32 v5, v10, v11
	global_store_dwordx4 v[24:25], v[2:5], off offset:256
	s_nop 1
	v_mul_f32_e32 v2, v7, v7
	v_mul_f32_e32 v3, v9, v9
	v_fmac_f32_e32 v2, v6, v6
	v_fmac_f32_e32 v3, v8, v8
	v_add_f32_e32 v2, v2, v3
	v_mul_f32_e32 v3, v13, v13
	v_mul_f32_e32 v4, v11, v11
	v_fmac_f32_e32 v3, v12, v12
	v_fmac_f32_e32 v4, v10, v10
	v_add_f32_e32 v3, v3, v4
	v_add_f32_e32 v2, v2, v3
	v_add_f32_e32 v2, v20, v2
	ds_bpermute_b32 v3, v151, v2
	s_waitcnt lgkmcnt(0)
	v_add_f32_e32 v2, v2, v3
	ds_bpermute_b32 v3, v150, v2
	s_and_saveexec_b64 s[10:11], s[38:39]
	s_cbranch_execz .LBB0_271
	v_lshlrev_b64 v[4:5], 7, v[18:19]
	v_lshl_add_u64 v[4:5], s[28:29], 0, v[4:5]
	v_lshl_add_u64 v[4:5], s[8:9], 2, v[4:5]
	s_lshl_b32 s56, s51, 2
	v_lshl_add_u64 v[4:5], v[4:5], 0, s[56:57]
	s_waitcnt lgkmcnt(0)
	v_add_f32_e32 v2, v2, v3
	ds_write_b32 v168, v2 offset:2816
.LBB0_271:
	s_or_b64 exec, exec, s[10:11]
	s_waitcnt lgkmcnt(0)
	s_barrier
	v_cmp_gt_u32_e32 vcc, 0x100, v0
	s_and_saveexec_b64 s[98:99], vcc
	s_cbranch_execz .Lss_skip_dn
	v_lshlrev_b32_e32 v172, 4, v0
	v_add_u32_e32 v172, 0x20400, v172
	ds_read_b128 v[176:179], v172
	s_lshl_b32 s10, s80, 8
	v_add_u32_e32 v170, s10, v0
	v_lshlrev_b32_e32 v170, 7, v170
	s_lshl_b32 s10, s8, 2
	v_add_u32_e32 v170, s10, v170
	v_mov_b32_e32 v171, 0
	v_lshl_add_u64 v[170:171], s[28:29], 0, v[170:171]
	s_waitcnt lgkmcnt(0)
	global_store_dwordx4 v[170:171], v[176:179], off
.Lss_skip_dn:
	s_or_b64 exec, exec, s[98:99]
	s_and_b64 vcc, exec, s[40:41]
	s_mov_b64 s[8:9], -1
	s_cbranch_vccnz .LBB0_238
	s_andn2_b64 vcc, exec, s[24:25]
	s_cbranch_vccnz .LBB0_237
	s_barrier
	s_branch .LBB0_237

; __device__ __forceinline__ u32x4 pack8(const f32x4 a, const f32x4 b) { u32x4 w; w.x = cvt_pk(a[0], a[1]); w.y = cvt_pk(a[2], a[3]); w.z = cvt_pk(b[0], b[1]); w.w = cvt_pk(b[2], b[3]); return w; }
; __device__ __forceinline__ f32x4 sigm4(f32x4 v) { f32x4 o; o[0] = sigm(v[0]); o[1] = sigm(v[1]); o[2] = sigm(v[2]); o[3] = sigm(v[3]); return o; }
; __device__ __forceinline__ float sq4(f32x4 v) { return (v[0] * v[0] + v[1] * v[1]) + (v[2] * v[2] + v[3] * v[3]); }
; #define EP_ROWLOOP for (int ai = 0; ai < 2; ++ai) _Pragma("unroll") for (int m = 0; m < 4; ++m)
;     __device__ __forceinline__ void operator()(const f32x4 (&acc)[2][2][4][2], const Unit& u, int wr, int wc, int fr, int fq) const {
;         const int rowb = u.pm * 256 + wr * 64 + fr, cb = u.pn * 256 + wc * 32 + 8 * fq;
; #pragma unroll
;         EP_ROWLOOP { EpFence fence_{(m & (EPB - 1)) == EPB - 1};
;             const int row = rowb + ai * 128 + m * 16;
;             float rs = 1.0f; if constexpr (MODE == 1) rs = rs_get<32>(rc, ssin, u.pm, wr * 64 + fr + ai * 128 + m * 16, fq, 1.0f / 2048.0f, 1e-6f);
;             float s = 0.f;
; #pragma unroll
;             for (int bj = 0; bj < 2; ++bj) {
;                 const size_t off = (size_t)row * 2048 + cb + bj * 128;
;                 f32x4 v0 = acc[ai][bj][m][0], v1 = acc[ai][bj][m][1], x0, x1;
;                 if constexpr (MODE == 1) { f32x4 e0, e1; unpack8(*(const u32x4*)(e + off), e0, e1); v0 = sigm4(v0 * rs) * e0; v1 = sigm4(v1 * rs) * e1; }
;                 unpack8(*(const u32x4*)(xold + off), x0, x1);
;                 v0 += x0; v1 += x1;
;                 *(u32x4*)(xnew + off) = pack8(v0, v1);
;                 s += sq4(v0) + sq4(v1);
;             }
;             s += __shfl_xor(s, 16); s += __shfl_xor(s, 32);
;             if (fq == 0) ssout[(size_t)row * 32 + u.pn * 4 + wc] = s;
.LBB0_479:
	v_lshrrev_b32_e32 v172, 6, v0
	v_lshrrev_b32_e32 v173, 2, v172
	v_and_b32_e32 v174, 3, v172
	v_and_b32_e32 v175, 15, v0
	v_lshl_add_u32 v168, v173, 6, v175
	v_lshlrev_b32_e32 v168, 4, v168
	v_lshl_add_u32 v168, v174, 2, v168
	v_add_u32_e32 v168, 0x20400, v168
	v_and_b32_e32 v144, 64, v190
	v_xor_b32_e32 v143, 16, v190
	v_add_u32_e32 v144, 64, v144
	v_cmp_lt_i32_e32 vcc, v143, v144
	v_lshl_add_u32 v142, s86, 8, v146
	v_lshl_or_b32 v140, s56, 8, v148
	v_cndmask_b32_e32 v143, v190, v143, vcc
	s_waitcnt vmcnt(0)
	v_lshlrev_b32_e32 v151, 2, v143
	v_xor_b32_e32 v143, 32, v190
	v_cmp_lt_i32_e32 vcc, v143, v144
	v_ashrrev_i32_e32 v141, 31, v140
	s_lshl_b32 s8, s56, 2
	v_cndmask_b32_e32 v143, v190, v143, vcc
	v_lshlrev_b32_e32 v150, 2, v143
	v_ashrrev_i32_e32 v143, 31, v142
	v_lshlrev_b64 v[144:145], 11, v[142:143]
	v_lshl_add_u64 v[144:145], v[144:145], 0, v[140:141]
	v_lshlrev_b64 v[144:145], 1, v[144:145]
	v_lshl_add_u64 v[152:153], s[26:27], 0, v[144:145]
	global_load_dwordx4 v[152:155], v[152:153], off
	s_ashr_i32 s9, s8, 31
	s_waitcnt vmcnt(0)
	v_lshlrev_b32_e32 v156, 16, v152
	v_and_b32_e32 v157, 0xffff0000, v152
	v_lshlrev_b32_e32 v152, 16, v153
	v_and_b32_e32 v153, 0xffff0000, v153
	v_lshlrev_b32_e32 v158, 16, v154
	v_and_b32_e32 v159, 0xffff0000, v154
	v_lshlrev_b32_e32 v154, 16, v155
	v_and_b32_e32 v155, 0xffff0000, v155
	v_pk_add_f32 v[152:153], v[124:125], v[152:153]
	v_pk_add_f32 v[156:157], v[122:123], v[156:157]
	v_pk_add_f32 v[128:129], v[128:129], v[154:155]
	v_pk_add_f32 v[126:127], v[126:127], v[158:159]
	v_cvt_pk_bf16_f32 v122, v156, v157
	v_cvt_pk_bf16_f32 v123, v152, v153
	v_cvt_pk_bf16_f32 v124, v126, v127
	v_cvt_pk_bf16_f32 v125, v128, v129
	v_lshl_add_u64 v[154:155], s[28:29], 0, v[144:145]
	global_store_dwordx4 v[154:155], v[122:125], off
	v_or_b32_e32 v144, 0x100, v144
	s_nop 0
	v_mul_f32_e32 v122, v157, v157
	v_mul_f32_e32 v123, v153, v153
	v_fmac_f32_e32 v122, v156, v156
	v_fmac_f32_e32 v123, v152, v152
	v_add_f32_e32 v122, v122, v123
	v_mul_f32_e32 v123, v127, v127
	v_mul_f32_e32 v124, v129, v129
	v_fmac_f32_e32 v123, v126, v126
	v_fmac_f32_e32 v124, v128, v128
	v_add_f32_e32 v123, v123, v124
	v_add_f32_e32 v152, v122, v123
	v_lshl_add_u64 v[122:123], s[26:27], 0, v[144:145]
	global_load_dwordx4 v[122:125], v[122:123], off
	s_waitcnt vmcnt(0)
	v_lshlrev_b32_e32 v126, 16, v122
	v_and_b32_e32 v127, 0xffff0000, v122
	v_lshlrev_b32_e32 v122, 16, v123
	v_and_b32_e32 v123, 0xffff0000, v123
	v_lshlrev_b32_e32 v128, 16, v124
	v_and_b32_e32 v129, 0xffff0000, v124
	v_lshlrev_b32_e32 v124, 16, v125
	v_and_b32_e32 v125, 0xffff0000, v125
	v_pk_add_f32 v[120:121], v[120:121], v[122:123]
	v_pk_add_f32 v[118:119], v[118:119], v[126:127]
	v_pk_add_f32 v[122:123], v[116:117], v[124:125]
	v_pk_add_f32 v[124:125], v[114:115], v[128:129]
	v_cvt_pk_bf16_f32 v114, v118, v119
	v_cvt_pk_bf16_f32 v115, v120, v121
	v_cvt_pk_bf16_f32 v116, v124, v125
	v_cvt_pk_bf16_f32 v117, v122, v123
	v_lshl_add_u64 v[126:127], s[28:29], 0, v[144:145]
	global_store_dwordx4 v[126:127], v[114:117], off
	s_nop 1
	v_mul_f32_e32 v114, v119, v119
	v_mul_f32_e32 v115, v121, v121
	v_fmac_f32_e32 v114, v118, v118
	v_fmac_f32_e32 v115, v120, v120
	v_add_f32_e32 v114, v114, v115
	v_mul_f32_e32 v115, v125, v125
	v_mul_f32_e32 v116, v123, v123
	v_fmac_f32_e32 v115, v124, v124
	v_fmac_f32_e32 v116, v122, v122
	v_add_f32_e32 v115, v115, v116
	v_add_f32_e32 v114, v114, v115
	v_add_f32_e32 v114, v152, v114
	ds_bpermute_b32 v115, v151, v114
	s_waitcnt lgkmcnt(0)
	v_add_f32_e32 v114, v114, v115
	ds_bpermute_b32 v115, v150, v114
	s_and_saveexec_b64 s[10:11], s[38:39]
	s_cbranch_execz .LBB0_481
	v_lshlrev_b64 v[116:117], 7, v[142:143]
	v_lshl_add_u64 v[116:117], s[30:31], 0, v[116:117]
	v_lshl_add_u64 v[116:117], s[8:9], 2, v[116:117]
	s_lshl_b32 s56, s75, 2
	v_lshl_add_u64 v[116:117], v[116:117], 0, s[56:57]
	s_waitcnt lgkmcnt(0)
	v_add_f32_e32 v114, v114, v115
	ds_write_b32 v168, v114
.LBB0_481:
	s_or_b64 exec, exec, s[10:11]
	v_or_b32_e32 v114, 16, v142
	s_waitcnt lgkmcnt(0)
	v_ashrrev_i32_e32 v115, 31, v114
	v_lshlrev_b64 v[116:117], 11, v[114:115]
	v_lshl_add_u64 v[116:117], v[116:117], 0, v[140:141]
	v_lshlrev_b64 v[116:117], 1, v[116:117]
	v_lshl_add_u64 v[118:119], s[26:27], 0, v[116:117]
	global_load_dwordx4 v[118:121], v[118:119], off
	s_waitcnt vmcnt(0)
	v_lshlrev_b32_e32 v122, 16, v118
	v_and_b32_e32 v123, 0xffff0000, v118
	v_lshlrev_b32_e32 v118, 16, v119
	v_and_b32_e32 v119, 0xffff0000, v119
	v_lshlrev_b32_e32 v124, 16, v120
	v_and_b32_e32 v125, 0xffff0000, v120
	v_lshlrev_b32_e32 v120, 16, v121
	v_and_b32_e32 v121, 0xffff0000, v121
	v_pk_add_f32 v[112:113], v[112:113], v[118:119]
	v_pk_add_f32 v[110:111], v[110:111], v[122:123]
	v_pk_add_f32 v[118:119], v[108:109], v[120:121]
	v_pk_add_f32 v[120:121], v[106:107], v[124:125]
	v_cvt_pk_bf16_f32 v106, v110, v111
	v_cvt_pk_bf16_f32 v107, v112, v113
	v_cvt_pk_bf16_f32 v108, v120, v121
	v_cvt_pk_bf16_f32 v109, v118, v119
	v_lshl_add_u64 v[122:123], s[28:29], 0, v[116:117]
	global_store_dwordx4 v[122:123], v[106:109], off
	v_or_b32_e32 v116, 0x100, v116
	s_nop 0
	v_mul_f32_e32 v106, v111, v111
	v_mul_f32_e32 v107, v113, v113
	v_fmac_f32_e32 v106, v110, v110
	v_fmac_f32_e32 v107, v112, v112
	v_add_f32_e32 v106, v106, v107
	v_mul_f32_e32 v107, v121, v121
	v_mul_f32_e32 v108, v119, v119
	v_fmac_f32_e32 v107, v120, v120
	v_fmac_f32_e32 v108, v118, v118
	v_add_f32_e32 v107, v107, v108
	v_add_f32_e32 v118, v106, v107
	v_lshl_add_u64 v[106:107], s[26:27], 0, v[116:117]
	global_load_dwordx4 v[106:109], v[106:107], off
	s_waitcnt vmcnt(0)
	v_lshlrev_b32_e32 v110, 16, v106
	v_and_b32_e32 v111, 0xffff0000, v106
	v_lshlrev_b32_e32 v106, 16, v107
	v_and_b32_e32 v107, 0xffff0000, v107
	v_lshlrev_b32_e32 v112, 16, v108
	v_and_b32_e32 v113, 0xffff0000, v108
	v_lshlrev_b32_e32 v108, 16, v109
	v_and_b32_e32 v109, 0xffff0000, v109
	v_pk_add_f32 v[104:105], v[104:105], v[106:107]
	v_pk_add_f32 v[102:103], v[102:103], v[110:111]
	v_pk_add_f32 v[106:107], v[100:101], v[108:109]
	v_pk_add_f32 v[108:109], v[98:99], v[112:113]
	v_cvt_pk_bf16_f32 v98, v102, v103
	v_cvt_pk_bf16_f32 v99, v104, v105
	v_cvt_pk_bf16_f32 v100, v108, v109
	v_cvt_pk_bf16_f32 v101, v106, v107
	v_lshl_add_u64 v[110:111], s[28:29], 0, v[116:117]
	global_store_dwordx4 v[110:111], v[98:101], off
	s_nop 1
	v_mul_f32_e32 v98, v103, v103
	v_mul_f32_e32 v99, v105, v105
	v_fmac_f32_e32 v98, v102, v102
	v_fmac_f32_e32 v99, v104, v104
	v_add_f32_e32 v98, v98, v99
	v_mul_f32_e32 v99, v109, v109
	v_mul_f32_e32 v100, v107, v107
	v_fmac_f32_e32 v99, v108, v108
	v_fmac_f32_e32 v100, v106, v106
	v_add_f32_e32 v99, v99, v100
	v_add_f32_e32 v98, v98, v99
	v_add_f32_e32 v98, v118, v98
	ds_bpermute_b32 v99, v151, v98
	s_waitcnt lgkmcnt(0)
	v_add_f32_e32 v98, v98, v99
	ds_bpermute_b32 v99, v150, v98
	s_and_saveexec_b64 s[10:11], s[38:39]
	s_cbranch_execz .LBB0_483
; __device__ __forceinline__ u32x4 pack8(const f32x4 a, const f32x4 b) { u32x4 w; w.x = cvt_pk(a[0], a[1]); w.y = cvt_pk(a[2], a[3]); w.z = cvt_pk(b[0], b[1]); w.w = cvt_pk(b[2], b[3]); return w; }
; __device__ __forceinline__ f32x4 sigm4(f32x4 v) { f32x4 o; o[0] = sigm(v[0]); o[1] = sigm(v[1]); o[2] = sigm(v[2]); o[3] = sigm(v[3]); return o; }
; __device__ __forceinline__ float sq4(f32x4 v) { return (v[0] * v[0] + v[1] * v[1]) + (v[2] * v[2] + v[3] * v[3]); }
; #define EP_ROWLOOP for (int ai = 0; ai < 2; ++ai) _Pragma("unroll") for (int m = 0; m < 4; ++m)
;     __device__ __forceinline__ void operator()(const f32x4 (&acc)[2][2][4][2], const Unit& u, int wr, int wc, int fr, int fq) const {
;         const int rowb = u.pm * 256 + wr * 64 + fr, cb = u.pn * 256 + wc * 32 + 8 * fq;
; #pragma unroll
;         EP_ROWLOOP { EpFence fence_{(m & (EPB - 1)) == EPB - 1};
;             const int row = rowb + ai * 128 + m * 16;
;             float rs = 1.0f; if constexpr (MODE == 1) rs = rs_get<32>(rc, ssin, u.pm, wr * 64 + fr + ai * 128 + m * 16, fq, 1.0f / 2048.0f, 1e-6f);
;             float s = 0.f;
; #pragma unroll
;             for (int bj = 0; bj < 2; ++bj) {
;                 const size_t off = (size_t)row * 2048 + cb + bj * 128;
;                 f32x4 v0 = acc[ai][bj][m][0], v1 = acc[ai][bj][m][1], x0, x1;
;                 if constexpr (MODE == 1) { f32x4 e0, e1; unpack8(*(const u32x4*)(e + off), e0, e1); v0 = sigm4(v0 * rs) * e0; v1 = sigm4(v1 * rs) * e1; }
;                 unpack8(*(const u32x4*)(xold + off), x0, x1);
;                 v0 += x0; v1 += x1;
;                 *(u32x4*)(xnew + off) = pack8(v0, v1);
;                 s += sq4(v0) + sq4(v1);
;             }
;             s += __shfl_xor(s, 16); s += __shfl_xor(s, 32);
;             if (fq == 0) ssout[(size_t)row * 32 + u.pn * 4 + wc] = s;
	v_lshlrev_b64 v[100:101], 7, v[114:115]
	v_lshl_add_u64 v[100:101], s[30:31], 0, v[100:101]
	v_lshl_add_u64 v[100:101], s[8:9], 2, v[100:101]
	s_lshl_b32 s56, s75, 2
	v_lshl_add_u64 v[100:101], v[100:101], 0, s[56:57]
	s_waitcnt lgkmcnt(0)
	v_add_f32_e32 v98, v98, v99
	ds_write_b32 v168, v98 offset:256
.LBB0_483:
	s_or_b64 exec, exec, s[10:11]
	v_or_b32_e32 v98, 32, v142
	s_waitcnt lgkmcnt(0)
	v_ashrrev_i32_e32 v99, 31, v98
	v_lshlrev_b64 v[100:101], 11, v[98:99]
	v_lshl_add_u64 v[100:101], v[100:101], 0, v[140:141]
	v_lshlrev_b64 v[100:101], 1, v[100:101]
	v_lshl_add_u64 v[102:103], s[26:27], 0, v[100:101]
	global_load_dwordx4 v[102:105], v[102:103], off
	s_waitcnt vmcnt(0)
	v_lshlrev_b32_e32 v106, 16, v102
	v_and_b32_e32 v107, 0xffff0000, v102
	v_lshlrev_b32_e32 v102, 16, v103
	v_and_b32_e32 v103, 0xffff0000, v103
	v_lshlrev_b32_e32 v108, 16, v104
	v_and_b32_e32 v109, 0xffff0000, v104
	v_lshlrev_b32_e32 v104, 16, v105
	v_and_b32_e32 v105, 0xffff0000, v105
	v_pk_add_f32 v[96:97], v[96:97], v[102:103]
	v_pk_add_f32 v[94:95], v[94:95], v[106:107]
	v_pk_add_f32 v[102:103], v[92:93], v[104:105]
	v_pk_add_f32 v[104:105], v[90:91], v[108:109]
	v_cvt_pk_bf16_f32 v90, v94, v95
	v_cvt_pk_bf16_f32 v91, v96, v97
	v_cvt_pk_bf16_f32 v92, v104, v105
	v_cvt_pk_bf16_f32 v93, v102, v103
	v_lshl_add_u64 v[106:107], s[28:29], 0, v[100:101]
	global_store_dwordx4 v[106:107], v[90:93], off
	v_or_b32_e32 v100, 0x100, v100
	s_nop 0
	v_mul_f32_e32 v90, v95, v95
	v_mul_f32_e32 v91, v97, v97
	v_fmac_f32_e32 v90, v94, v94
	v_fmac_f32_e32 v91, v96, v96
	v_add_f32_e32 v90, v90, v91
	v_mul_f32_e32 v91, v105, v105
	v_mul_f32_e32 v92, v103, v103
	v_fmac_f32_e32 v91, v104, v104
	v_fmac_f32_e32 v92, v102, v102
	v_add_f32_e32 v91, v91, v92
	v_add_f32_e32 v102, v90, v91
	v_lshl_add_u64 v[90:91], s[26:27], 0, v[100:101]
	global_load_dwordx4 v[90:93], v[90:91], off
	s_waitcnt vmcnt(0)
	v_lshlrev_b32_e32 v94, 16, v90
	v_and_b32_e32 v95, 0xffff0000, v90
	v_lshlrev_b32_e32 v90, 16, v91
	v_and_b32_e32 v91, 0xffff0000, v91
	v_lshlrev_b32_e32 v96, 16, v92
	v_and_b32_e32 v97, 0xffff0000, v92
	v_lshlrev_b32_e32 v92, 16, v93
	v_and_b32_e32 v93, 0xffff0000, v93
	v_pk_add_f32 v[88:89], v[88:89], v[90:91]
	v_pk_add_f32 v[86:87], v[86:87], v[94:95]
	v_pk_add_f32 v[90:91], v[84:85], v[92:93]
	v_pk_add_f32 v[92:93], v[82:83], v[96:97]
	v_cvt_pk_bf16_f32 v82, v86, v87
	v_cvt_pk_bf16_f32 v83, v88, v89
	v_cvt_pk_bf16_f32 v84, v92, v93
	v_cvt_pk_bf16_f32 v85, v90, v91
	v_lshl_add_u64 v[94:95], s[28:29], 0, v[100:101]
	global_store_dwordx4 v[94:95], v[82:85], off
	s_nop 1
	v_mul_f32_e32 v82, v87, v87
	v_mul_f32_e32 v83, v89, v89
	v_fmac_f32_e32 v82, v86, v86
	v_fmac_f32_e32 v83, v88, v88
	v_add_f32_e32 v82, v82, v83
	v_mul_f32_e32 v83, v93, v93
	v_mul_f32_e32 v84, v91, v91
	v_fmac_f32_e32 v83, v92, v92
	v_fmac_f32_e32 v84, v90, v90
	v_add_f32_e32 v83, v83, v84
	v_add_f32_e32 v82, v82, v83
	v_add_f32_e32 v82, v102, v82
	ds_bpermute_b32 v83, v151, v82
	s_waitcnt lgkmcnt(0)
	v_add_f32_e32 v82, v82, v83
	ds_bpermute_b32 v83, v150, v82
	s_and_saveexec_b64 s[10:11], s[38:39]
	s_cbranch_execz .LBB0_485
	v_lshlrev_b64 v[84:85], 7, v[98:99]
	v_lshl_add_u64 v[84:85], s[30:31], 0, v[84:85]
	v_lshl_add_u64 v[84:85], s[8:9], 2, v[84:85]
	s_lshl_b32 s56, s75, 2
	v_lshl_add_u64 v[84:85], v[84:85], 0, s[56:57]
	s_waitcnt lgkmcnt(0)
	v_add_f32_e32 v82, v82, v83
	ds_write_b32 v168, v82 offset:512
.LBB0_485:
	s_or_b64 exec, exec, s[10:11]
	v_or_b32_e32 v82, 48, v142
	s_waitcnt lgkmcnt(0)
	v_ashrrev_i32_e32 v83, 31, v82
	v_lshlrev_b64 v[84:85], 11, v[82:83]
	v_lshl_add_u64 v[84:85], v[84:85], 0, v[140:141]
	v_lshlrev_b64 v[84:85], 1, v[84:85]
	v_lshl_add_u64 v[86:87], s[26:27], 0, v[84:85]
	global_load_dwordx4 v[86:89], v[86:87], off
	s_waitcnt vmcnt(0)
	v_lshlrev_b32_e32 v90, 16, v86
	v_and_b32_e32 v91, 0xffff0000, v86
	v_lshlrev_b32_e32 v86, 16, v87
	v_and_b32_e32 v87, 0xffff0000, v87
	v_lshlrev_b32_e32 v92, 16, v88
	v_and_b32_e32 v93, 0xffff0000, v88
	v_lshlrev_b32_e32 v88, 16, v89
	v_and_b32_e32 v89, 0xffff0000, v89
	v_pk_add_f32 v[80:81], v[80:81], v[86:87]
	v_pk_add_f32 v[78:79], v[78:79], v[90:91]
	v_pk_add_f32 v[86:87], v[76:77], v[88:89]
	v_pk_add_f32 v[88:89], v[74:75], v[92:93]
	v_cvt_pk_bf16_f32 v74, v78, v79
	v_cvt_pk_bf16_f32 v75, v80, v81
	v_cvt_pk_bf16_f32 v76, v88, v89
	v_cvt_pk_bf16_f32 v77, v86, v87
	v_lshl_add_u64 v[90:91], s[28:29], 0, v[84:85]
	global_store_dwordx4 v[90:91], v[74:77], off
	v_or_b32_e32 v84, 0x100, v84
	s_nop 0
	v_mul_f32_e32 v74, v79, v79
	v_mul_f32_e32 v75, v81, v81
	v_fmac_f32_e32 v74, v78, v78
	v_fmac_f32_e32 v75, v80, v80
	v_add_f32_e32 v74, v74, v75
	v_mul_f32_e32 v75, v89, v89
	v_mul_f32_e32 v76, v87, v87
	v_fmac_f32_e32 v75, v88, v88
	v_fmac_f32_e32 v76, v86, v86
	v_add_f32_e32 v75, v75, v76
	v_add_f32_e32 v86, v74, v75
	v_lshl_add_u64 v[74:75], s[26:27], 0, v[84:85]
	global_load_dwordx4 v[74:77], v[74:75], off
	s_waitcnt vmcnt(0)
	v_lshlrev_b32_e32 v78, 16, v74
	v_and_b32_e32 v79, 0xffff0000, v74
	v_lshlrev_b32_e32 v74, 16, v75
	v_and_b32_e32 v75, 0xffff0000, v75
	v_lshlrev_b32_e32 v80, 16, v76
	v_and_b32_e32 v81, 0xffff0000, v76
	v_lshlrev_b32_e32 v76, 16, v77
	v_and_b32_e32 v77, 0xffff0000, v77
	v_pk_add_f32 v[72:73], v[72:73], v[74:75]
	v_pk_add_f32 v[70:71], v[70:71], v[78:79]
	v_pk_add_f32 v[74:75], v[68:69], v[76:77]
	v_pk_add_f32 v[76:77], v[66:67], v[80:81]
	v_cvt_pk_bf16_f32 v66, v70, v71
	v_cvt_pk_bf16_f32 v67, v72, v73
	v_cvt_pk_bf16_f32 v68, v76, v77
	v_cvt_pk_bf16_f32 v69, v74, v75
	v_lshl_add_u64 v[78:79], s[28:29], 0, v[84:85]
	global_store_dwordx4 v[78:79], v[66:69], off
	s_nop 1
	v_mul_f32_e32 v66, v71, v71
	v_mul_f32_e32 v67, v73, v73
	v_fmac_f32_e32 v66, v70, v70
	v_fmac_f32_e32 v67, v72, v72
	v_add_f32_e32 v66, v66, v67
	v_mul_f32_e32 v67, v77, v77
	v_mul_f32_e32 v68, v75, v75
	v_fmac_f32_e32 v67, v76, v76
	v_fmac_f32_e32 v68, v74, v74
	v_add_f32_e32 v67, v67, v68
	v_add_f32_e32 v66, v66, v67
	v_add_f32_e32 v66, v86, v66
	ds_bpermute_b32 v67, v151, v66
	s_waitcnt lgkmcnt(0)
	v_add_f32_e32 v66, v66, v67
	ds_bpermute_b32 v67, v150, v66
	s_and_saveexec_b64 s[10:11], s[38:39]
	s_cbranch_execz .LBB0_487
	v_lshlrev_b64 v[68:69], 7, v[82:83]
	v_lshl_add_u64 v[68:69], s[30:31], 0, v[68:69]
	v_lshl_add_u64 v[68:69], s[8:9], 2, v[68:69]
	s_lshl_b32 s56, s75, 2
	v_lshl_add_u64 v[68:69], v[68:69], 0, s[56:57]
	s_waitcnt lgkmcnt(0)
	v_add_f32_e32 v66, v66, v67
	ds_write_b32 v168, v66 offset:768
; __device__ __forceinline__ u32x4 pack8(const f32x4 a, const f32x4 b) { u32x4 w; w.x = cvt_pk(a[0], a[1]); w.y = cvt_pk(a[2], a[3]); w.z = cvt_pk(b[0], b[1]); w.w = cvt_pk(b[2], b[3]); return w; }
; __device__ __forceinline__ f32x4 sigm4(f32x4 v) { f32x4 o; o[0] = sigm(v[0]); o[1] = sigm(v[1]); o[2] = sigm(v[2]); o[3] = sigm(v[3]); return o; }
; __device__ __forceinline__ float sq4(f32x4 v) { return (v[0] * v[0] + v[1] * v[1]) + (v[2] * v[2] + v[3] * v[3]); }
; #define EP_ROWLOOP for (int ai = 0; ai < 2; ++ai) _Pragma("unroll") for (int m = 0; m < 4; ++m)
;     __device__ __forceinline__ void operator()(const f32x4 (&acc)[2][2][4][2], const Unit& u, int wr, int wc, int fr, int fq) const {
;         const int rowb = u.pm * 256 + wr * 64 + fr, cb = u.pn * 256 + wc * 32 + 8 * fq;
; #pragma unroll
;         EP_ROWLOOP { EpFence fence_{(m & (EPB - 1)) == EPB - 1};
;             const int row = rowb + ai * 128 + m * 16;
;             float rs = 1.0f; if constexpr (MODE == 1) rs = rs_get<32>(rc, ssin, u.pm, wr * 64 + fr + ai * 128 + m * 16, fq, 1.0f / 2048.0f, 1e-6f);
;             float s = 0.f;
; #pragma unroll
;             for (int bj = 0; bj < 2; ++bj) {
;                 const size_t off = (size_t)row * 2048 + cb + bj * 128;
;                 f32x4 v0 = acc[ai][bj][m][0], v1 = acc[ai][bj][m][1], x0, x1;
;                 if constexpr (MODE == 1) { f32x4 e0, e1; unpack8(*(const u32x4*)(e + off), e0, e1); v0 = sigm4(v0 * rs) * e0; v1 = sigm4(v1 * rs) * e1; }
;                 unpack8(*(const u32x4*)(xold + off), x0, x1);
;                 v0 += x0; v1 += x1;
;                 *(u32x4*)(xnew + off) = pack8(v0, v1);
;                 s += sq4(v0) + sq4(v1);
;             }
;             s += __shfl_xor(s, 16); s += __shfl_xor(s, 32);
;             if (fq == 0) ssout[(size_t)row * 32 + u.pn * 4 + wc] = s;
.LBB0_487:
	s_or_b64 exec, exec, s[10:11]
	v_add_u32_e32 v66, 0x80, v142
	s_waitcnt lgkmcnt(0)
	v_ashrrev_i32_e32 v67, 31, v66
	v_lshlrev_b64 v[68:69], 11, v[66:67]
	v_lshl_add_u64 v[68:69], v[68:69], 0, v[140:141]
	v_lshlrev_b64 v[68:69], 1, v[68:69]
	v_lshl_add_u64 v[70:71], s[26:27], 0, v[68:69]
	global_load_dwordx4 v[70:73], v[70:71], off
	s_waitcnt vmcnt(0)
	v_lshlrev_b32_e32 v74, 16, v70
	v_and_b32_e32 v75, 0xffff0000, v70
	v_lshlrev_b32_e32 v70, 16, v71
	v_and_b32_e32 v71, 0xffff0000, v71
	v_lshlrev_b32_e32 v76, 16, v72
	v_and_b32_e32 v77, 0xffff0000, v72
	v_lshlrev_b32_e32 v72, 16, v73
	v_and_b32_e32 v73, 0xffff0000, v73
	v_pk_add_f32 v[64:65], v[64:65], v[70:71]
	v_pk_add_f32 v[62:63], v[62:63], v[74:75]
	v_pk_add_f32 v[70:71], v[60:61], v[72:73]
	v_pk_add_f32 v[72:73], v[58:59], v[76:77]
	v_cvt_pk_bf16_f32 v58, v62, v63
	v_cvt_pk_bf16_f32 v59, v64, v65
	v_cvt_pk_bf16_f32 v60, v72, v73
	v_cvt_pk_bf16_f32 v61, v70, v71
	v_lshl_add_u64 v[74:75], s[28:29], 0, v[68:69]
	global_store_dwordx4 v[74:75], v[58:61], off
	v_or_b32_e32 v68, 0x100, v68
	s_nop 0
	v_mul_f32_e32 v58, v63, v63
	v_mul_f32_e32 v59, v65, v65
	v_fmac_f32_e32 v58, v62, v62
	v_fmac_f32_e32 v59, v64, v64
	v_add_f32_e32 v58, v58, v59
	v_mul_f32_e32 v59, v73, v73
	v_mul_f32_e32 v60, v71, v71
	v_fmac_f32_e32 v59, v72, v72
	v_fmac_f32_e32 v60, v70, v70
	v_add_f32_e32 v59, v59, v60
	v_add_f32_e32 v70, v58, v59
	v_lshl_add_u64 v[58:59], s[26:27], 0, v[68:69]
	global_load_dwordx4 v[58:61], v[58:59], off
	s_waitcnt vmcnt(0)
	v_lshlrev_b32_e32 v62, 16, v58
	v_and_b32_e32 v63, 0xffff0000, v58
	v_lshlrev_b32_e32 v58, 16, v59
	v_and_b32_e32 v59, 0xffff0000, v59
	v_lshlrev_b32_e32 v64, 16, v60
	v_and_b32_e32 v65, 0xffff0000, v60
	v_lshlrev_b32_e32 v60, 16, v61
	v_and_b32_e32 v61, 0xffff0000, v61
	v_pk_add_f32 v[56:57], v[56:57], v[58:59]
	v_pk_add_f32 v[54:55], v[54:55], v[62:63]
	v_pk_add_f32 v[58:59], v[52:53], v[60:61]
	v_pk_add_f32 v[60:61], v[50:51], v[64:65]
	v_cvt_pk_bf16_f32 v50, v54, v55
	v_cvt_pk_bf16_f32 v51, v56, v57
	v_cvt_pk_bf16_f32 v52, v60, v61
	v_cvt_pk_bf16_f32 v53, v58, v59
	v_lshl_add_u64 v[62:63], s[28:29], 0, v[68:69]
	global_store_dwordx4 v[62:63], v[50:53], off
	s_nop 1
	v_mul_f32_e32 v50, v55, v55
	v_mul_f32_e32 v51, v57, v57
	v_fmac_f32_e32 v50, v54, v54
	v_fmac_f32_e32 v51, v56, v56
	v_add_f32_e32 v50, v50, v51
	v_mul_f32_e32 v51, v61, v61
	v_mul_f32_e32 v52, v59, v59
	v_fmac_f32_e32 v51, v60, v60
	v_fmac_f32_e32 v52, v58, v58
	v_add_f32_e32 v51, v51, v52
	v_add_f32_e32 v50, v50, v51
	v_add_f32_e32 v50, v70, v50
	ds_bpermute_b32 v51, v151, v50
	s_waitcnt lgkmcnt(0)
	v_add_f32_e32 v50, v50, v51
	ds_bpermute_b32 v51, v150, v50
	s_and_saveexec_b64 s[10:11], s[38:39]
	s_cbranch_execz .LBB0_489
	v_lshlrev_b64 v[52:53], 7, v[66:67]
	v_lshl_add_u64 v[52:53], s[30:31], 0, v[52:53]
	v_lshl_add_u64 v[52:53], s[8:9], 2, v[52:53]
	s_lshl_b32 s56, s75, 2
	v_lshl_add_u64 v[52:53], v[52:53], 0, s[56:57]
	s_waitcnt lgkmcnt(0)
	v_add_f32_e32 v50, v50, v51
	ds_write_b32 v168, v50 offset:2048
.LBB0_489:
	s_or_b64 exec, exec, s[10:11]
	v_add_u32_e32 v50, 0x90, v142
	s_waitcnt lgkmcnt(0)
	v_ashrrev_i32_e32 v51, 31, v50
	v_lshlrev_b64 v[52:53], 11, v[50:51]
	v_lshl_add_u64 v[52:53], v[52:53], 0, v[140:141]
	v_lshlrev_b64 v[52:53], 1, v[52:53]
	v_lshl_add_u64 v[54:55], s[26:27], 0, v[52:53]
	global_load_dwordx4 v[54:57], v[54:55], off
	s_waitcnt vmcnt(0)
	v_lshlrev_b32_e32 v58, 16, v54
	v_and_b32_e32 v59, 0xffff0000, v54
	v_lshlrev_b32_e32 v54, 16, v55
	v_and_b32_e32 v55, 0xffff0000, v55
	v_lshlrev_b32_e32 v60, 16, v56
	v_and_b32_e32 v61, 0xffff0000, v56
	v_lshlrev_b32_e32 v56, 16, v57
	v_and_b32_e32 v57, 0xffff0000, v57
	v_pk_add_f32 v[48:49], v[48:49], v[54:55]
	v_pk_add_f32 v[46:47], v[46:47], v[58:59]
	v_pk_add_f32 v[54:55], v[44:45], v[56:57]
	v_pk_add_f32 v[56:57], v[42:43], v[60:61]
	v_cvt_pk_bf16_f32 v42, v46, v47
	v_cvt_pk_bf16_f32 v43, v48, v49
	v_cvt_pk_bf16_f32 v44, v56, v57
	v_cvt_pk_bf16_f32 v45, v54, v55
	v_lshl_add_u64 v[58:59], s[28:29], 0, v[52:53]
	global_store_dwordx4 v[58:59], v[42:45], off
	v_or_b32_e32 v52, 0x100, v52
	s_nop 0
	v_mul_f32_e32 v42, v47, v47
	v_mul_f32_e32 v43, v49, v49
	v_fmac_f32_e32 v42, v46, v46
	v_fmac_f32_e32 v43, v48, v48
	v_add_f32_e32 v42, v42, v43
	v_mul_f32_e32 v43, v57, v57
	v_mul_f32_e32 v44, v55, v55
	v_fmac_f32_e32 v43, v56, v56
	v_fmac_f32_e32 v44, v54, v54
	v_add_f32_e32 v43, v43, v44
	v_add_f32_e32 v54, v42, v43
	v_lshl_add_u64 v[42:43], s[26:27], 0, v[52:53]
	global_load_dwordx4 v[42:45], v[42:43], off
	s_waitcnt vmcnt(0)
	v_lshlrev_b32_e32 v46, 16, v42
	v_and_b32_e32 v47, 0xffff0000, v42
	v_lshlrev_b32_e32 v42, 16, v43
	v_and_b32_e32 v43, 0xffff0000, v43
	v_lshlrev_b32_e32 v48, 16, v44
	v_and_b32_e32 v49, 0xffff0000, v44
	v_lshlrev_b32_e32 v44, 16, v45
	v_and_b32_e32 v45, 0xffff0000, v45
	v_pk_add_f32 v[40:41], v[40:41], v[42:43]
	v_pk_add_f32 v[38:39], v[38:39], v[46:47]
	v_pk_add_f32 v[42:43], v[36:37], v[44:45]
	v_pk_add_f32 v[44:45], v[34:35], v[48:49]
	v_cvt_pk_bf16_f32 v34, v38, v39
	v_cvt_pk_bf16_f32 v35, v40, v41
	v_cvt_pk_bf16_f32 v36, v44, v45
	v_cvt_pk_bf16_f32 v37, v42, v43
	v_lshl_add_u64 v[46:47], s[28:29], 0, v[52:53]
	global_store_dwordx4 v[46:47], v[34:37], off
	s_nop 1
	v_mul_f32_e32 v34, v39, v39
	v_mul_f32_e32 v35, v41, v41
	v_fmac_f32_e32 v34, v38, v38
	v_fmac_f32_e32 v35, v40, v40
	v_add_f32_e32 v34, v34, v35
	v_mul_f32_e32 v35, v45, v45
	v_mul_f32_e32 v36, v43, v43
	v_fmac_f32_e32 v35, v44, v44
	v_fmac_f32_e32 v36, v42, v42
	v_add_f32_e32 v35, v35, v36
	v_add_f32_e32 v34, v34, v35
	v_add_f32_e32 v34, v54, v34
	ds_bpermute_b32 v35, v151, v34
	s_waitcnt lgkmcnt(0)
	v_add_f32_e32 v34, v34, v35
	ds_bpermute_b32 v35, v150, v34
	s_and_saveexec_b64 s[10:11], s[38:39]
	s_cbranch_execz .LBB0_491
	v_lshlrev_b64 v[36:37], 7, v[50:51]
	v_lshl_add_u64 v[36:37], s[30:31], 0, v[36:37]
	v_lshl_add_u64 v[36:37], s[8:9], 2, v[36:37]
	s_lshl_b32 s56, s75, 2
	v_lshl_add_u64 v[36:37], v[36:37], 0, s[56:57]
	s_waitcnt lgkmcnt(0)
	v_add_f32_e32 v34, v34, v35
	ds_write_b32 v168, v34 offset:2304
; __device__ __forceinline__ u32x4 pack8(const f32x4 a, const f32x4 b) { u32x4 w; w.x = cvt_pk(a[0], a[1]); w.y = cvt_pk(a[2], a[3]); w.z = cvt_pk(b[0], b[1]); w.w = cvt_pk(b[2], b[3]); return w; }
; __device__ __forceinline__ f32x4 sigm4(f32x4 v) { f32x4 o; o[0] = sigm(v[0]); o[1] = sigm(v[1]); o[2] = sigm(v[2]); o[3] = sigm(v[3]); return o; }
; __device__ __forceinline__ float sq4(f32x4 v) { return (v[0] * v[0] + v[1] * v[1]) + (v[2] * v[2] + v[3] * v[3]); }
; #define EP_ROWLOOP for (int ai = 0; ai < 2; ++ai) _Pragma("unroll") for (int m = 0; m < 4; ++m)
;     __device__ __forceinline__ void operator()(const f32x4 (&acc)[2][2][4][2], const Unit& u, int wr, int wc, int fr, int fq) const {
;         const int rowb = u.pm * 256 + wr * 64 + fr, cb = u.pn * 256 + wc * 32 + 8 * fq;
; #pragma unroll
;         EP_ROWLOOP { EpFence fence_{(m & (EPB - 1)) == EPB - 1};
;             const int row = rowb + ai * 128 + m * 16;
;             float rs = 1.0f; if constexpr (MODE == 1) rs = rs_get<32>(rc, ssin, u.pm, wr * 64 + fr + ai * 128 + m * 16, fq, 1.0f / 2048.0f, 1e-6f);
;             float s = 0.f;
; #pragma unroll
;             for (int bj = 0; bj < 2; ++bj) {
;                 const size_t off = (size_t)row * 2048 + cb + bj * 128;
;                 f32x4 v0 = acc[ai][bj][m][0], v1 = acc[ai][bj][m][1], x0, x1;
;                 if constexpr (MODE == 1) { f32x4 e0, e1; unpack8(*(const u32x4*)(e + off), e0, e1); v0 = sigm4(v0 * rs) * e0; v1 = sigm4(v1 * rs) * e1; }
;                 unpack8(*(const u32x4*)(xold + off), x0, x1);
;                 v0 += x0; v1 += x1;
;                 *(u32x4*)(xnew + off) = pack8(v0, v1);
;                 s += sq4(v0) + sq4(v1);
;             }
;             s += __shfl_xor(s, 16); s += __shfl_xor(s, 32);
;             if (fq == 0) ssout[(size_t)row * 32 + u.pn * 4 + wc] = s;
.LBB0_491:
	s_or_b64 exec, exec, s[10:11]
	v_add_u32_e32 v34, 0xa0, v142
	s_waitcnt lgkmcnt(0)
	v_ashrrev_i32_e32 v35, 31, v34
	v_lshlrev_b64 v[36:37], 11, v[34:35]
	v_lshl_add_u64 v[36:37], v[36:37], 0, v[140:141]
	v_lshlrev_b64 v[36:37], 1, v[36:37]
	v_lshl_add_u64 v[38:39], s[26:27], 0, v[36:37]
	global_load_dwordx4 v[38:41], v[38:39], off
	s_waitcnt vmcnt(0)
	v_lshlrev_b32_e32 v42, 16, v38
	v_and_b32_e32 v43, 0xffff0000, v38
	v_lshlrev_b32_e32 v38, 16, v39
	v_and_b32_e32 v39, 0xffff0000, v39
	v_lshlrev_b32_e32 v44, 16, v40
	v_and_b32_e32 v45, 0xffff0000, v40
	v_lshlrev_b32_e32 v40, 16, v41
	v_and_b32_e32 v41, 0xffff0000, v41
	v_pk_add_f32 v[32:33], v[32:33], v[38:39]
	v_pk_add_f32 v[30:31], v[30:31], v[42:43]
	v_pk_add_f32 v[38:39], v[28:29], v[40:41]
	v_pk_add_f32 v[40:41], v[26:27], v[44:45]
	v_cvt_pk_bf16_f32 v26, v30, v31
	v_cvt_pk_bf16_f32 v27, v32, v33
	v_cvt_pk_bf16_f32 v28, v40, v41
	v_cvt_pk_bf16_f32 v29, v38, v39
	v_lshl_add_u64 v[42:43], s[28:29], 0, v[36:37]
	global_store_dwordx4 v[42:43], v[26:29], off
	v_or_b32_e32 v36, 0x100, v36
	s_nop 0
	v_mul_f32_e32 v26, v31, v31
	v_mul_f32_e32 v27, v33, v33
	v_fmac_f32_e32 v26, v30, v30
	v_fmac_f32_e32 v27, v32, v32
	v_add_f32_e32 v26, v26, v27
	v_mul_f32_e32 v27, v41, v41
	v_mul_f32_e32 v28, v39, v39
	v_fmac_f32_e32 v27, v40, v40
	v_fmac_f32_e32 v28, v38, v38
	v_add_f32_e32 v27, v27, v28
	v_add_f32_e32 v38, v26, v27
	v_lshl_add_u64 v[26:27], s[26:27], 0, v[36:37]
	global_load_dwordx4 v[26:29], v[26:27], off
	s_waitcnt vmcnt(0)
	v_lshlrev_b32_e32 v30, 16, v26
	v_and_b32_e32 v31, 0xffff0000, v26
	v_lshlrev_b32_e32 v26, 16, v27
	v_and_b32_e32 v27, 0xffff0000, v27
	v_lshlrev_b32_e32 v32, 16, v28
	v_and_b32_e32 v33, 0xffff0000, v28
	v_lshlrev_b32_e32 v28, 16, v29
	v_and_b32_e32 v29, 0xffff0000, v29
	v_pk_add_f32 v[24:25], v[24:25], v[26:27]
	v_pk_add_f32 v[22:23], v[22:23], v[30:31]
	v_pk_add_f32 v[26:27], v[20:21], v[28:29]
	v_pk_add_f32 v[28:29], v[18:19], v[32:33]
	v_cvt_pk_bf16_f32 v18, v22, v23
	v_cvt_pk_bf16_f32 v19, v24, v25
	v_cvt_pk_bf16_f32 v20, v28, v29
	v_cvt_pk_bf16_f32 v21, v26, v27
	v_lshl_add_u64 v[30:31], s[28:29], 0, v[36:37]
	global_store_dwordx4 v[30:31], v[18:21], off
	s_nop 1
	v_mul_f32_e32 v18, v23, v23
	v_mul_f32_e32 v19, v25, v25
	v_fmac_f32_e32 v18, v22, v22
	v_fmac_f32_e32 v19, v24, v24
	v_add_f32_e32 v18, v18, v19
	v_mul_f32_e32 v19, v29, v29
	v_mul_f32_e32 v20, v27, v27
	v_fmac_f32_e32 v19, v28, v28
	v_fmac_f32_e32 v20, v26, v26
	v_add_f32_e32 v19, v19, v20
	v_add_f32_e32 v18, v18, v19
	v_add_f32_e32 v18, v38, v18
	ds_bpermute_b32 v19, v151, v18
	s_waitcnt lgkmcnt(0)
	v_add_f32_e32 v18, v18, v19
	ds_bpermute_b32 v19, v150, v18
	s_and_saveexec_b64 s[10:11], s[38:39]
	s_cbranch_execz .LBB0_493
	v_lshlrev_b64 v[20:21], 7, v[34:35]
	v_lshl_add_u64 v[20:21], s[30:31], 0, v[20:21]
	v_lshl_add_u64 v[20:21], s[8:9], 2, v[20:21]
	s_lshl_b32 s56, s75, 2
	v_lshl_add_u64 v[20:21], v[20:21], 0, s[56:57]
	s_waitcnt lgkmcnt(0)
	v_add_f32_e32 v18, v18, v19
	ds_write_b32 v168, v18 offset:2560
.LBB0_493:
	s_or_b64 exec, exec, s[10:11]
	v_add_u32_e32 v18, 0xb0, v142
	s_waitcnt lgkmcnt(0)
	v_ashrrev_i32_e32 v19, 31, v18
	v_lshlrev_b64 v[20:21], 11, v[18:19]
	v_lshl_add_u64 v[20:21], v[20:21], 0, v[140:141]
	v_lshlrev_b64 v[20:21], 1, v[20:21]
	v_lshl_add_u64 v[22:23], s[26:27], 0, v[20:21]
	global_load_dwordx4 v[22:25], v[22:23], off
	s_waitcnt vmcnt(0)
	v_lshlrev_b32_e32 v26, 16, v22
	v_and_b32_e32 v27, 0xffff0000, v22
	v_lshlrev_b32_e32 v22, 16, v23
	v_and_b32_e32 v23, 0xffff0000, v23
	v_lshlrev_b32_e32 v28, 16, v24
	v_and_b32_e32 v29, 0xffff0000, v24
	v_lshlrev_b32_e32 v24, 16, v25
	v_and_b32_e32 v25, 0xffff0000, v25
	v_pk_add_f32 v[16:17], v[16:17], v[22:23]
	v_pk_add_f32 v[14:15], v[14:15], v[26:27]
	v_pk_add_f32 v[22:23], v[12:13], v[24:25]
	v_pk_add_f32 v[24:25], v[10:11], v[28:29]
	v_cvt_pk_bf16_f32 v10, v14, v15
	v_cvt_pk_bf16_f32 v11, v16, v17
	v_cvt_pk_bf16_f32 v12, v24, v25
	v_cvt_pk_bf16_f32 v13, v22, v23
	v_lshl_add_u64 v[26:27], s[28:29], 0, v[20:21]
	global_store_dwordx4 v[26:27], v[10:13], off
	v_or_b32_e32 v20, 0x100, v20
	s_nop 0
	v_mul_f32_e32 v10, v15, v15
	v_mul_f32_e32 v11, v17, v17
	v_fmac_f32_e32 v10, v14, v14
	v_fmac_f32_e32 v11, v16, v16
	v_add_f32_e32 v10, v10, v11
	v_mul_f32_e32 v11, v25, v25
	v_mul_f32_e32 v12, v23, v23
	v_fmac_f32_e32 v11, v24, v24
	v_fmac_f32_e32 v12, v22, v22
	v_add_f32_e32 v11, v11, v12
	v_add_f32_e32 v22, v10, v11
	v_lshl_add_u64 v[10:11], s[26:27], 0, v[20:21]
	global_load_dwordx4 v[10:13], v[10:11], off
	s_waitcnt vmcnt(0)
	v_lshlrev_b32_e32 v14, 16, v10
	v_and_b32_e32 v15, 0xffff0000, v10
	v_lshlrev_b32_e32 v10, 16, v11
	v_and_b32_e32 v11, 0xffff0000, v11
	v_lshlrev_b32_e32 v16, 16, v12
	v_and_b32_e32 v17, 0xffff0000, v12
	v_lshlrev_b32_e32 v12, 16, v13
	v_and_b32_e32 v13, 0xffff0000, v13
	v_pk_add_f32 v[8:9], v[8:9], v[10:11]
	v_pk_add_f32 v[6:7], v[6:7], v[14:15]
	v_pk_add_f32 v[10:11], v[4:5], v[12:13]
	v_pk_add_f32 v[12:13], v[2:3], v[16:17]
	v_cvt_pk_bf16_f32 v2, v6, v7
	v_cvt_pk_bf16_f32 v3, v8, v9
	v_cvt_pk_bf16_f32 v4, v12, v13
	v_cvt_pk_bf16_f32 v5, v10, v11
	v_lshl_add_u64 v[14:15], s[28:29], 0, v[20:21]
	global_store_dwordx4 v[14:15], v[2:5], off
	s_nop 1
	v_mul_f32_e32 v2, v7, v7
	v_mul_f32_e32 v3, v9, v9
	v_fmac_f32_e32 v2, v6, v6
	v_fmac_f32_e32 v3, v8, v8
	v_add_f32_e32 v2, v2, v3
	v_mul_f32_e32 v3, v13, v13
	v_mul_f32_e32 v4, v11, v11
	v_fmac_f32_e32 v3, v12, v12
	v_fmac_f32_e32 v4, v10, v10
	v_add_f32_e32 v3, v3, v4
	v_add_f32_e32 v2, v2, v3
	v_add_f32_e32 v2, v22, v2
	ds_bpermute_b32 v3, v151, v2
	s_waitcnt lgkmcnt(0)
	v_add_f32_e32 v2, v2, v3
	ds_bpermute_b32 v3, v150, v2
	s_and_saveexec_b64 s[10:11], s[38:39]
	s_cbranch_execz .LBB0_495
	v_lshlrev_b64 v[4:5], 7, v[18:19]
	v_lshl_add_u64 v[4:5], s[30:31], 0, v[4:5]
	v_lshl_add_u64 v[4:5], s[8:9], 2, v[4:5]
	s_lshl_b32 s56, s75, 2
	v_lshl_add_u64 v[4:5], v[4:5], 0, s[56:57]
	s_waitcnt lgkmcnt(0)
	v_add_f32_e32 v2, v2, v3
	ds_write_b32 v168, v2 offset:2816
.LBB0_495:
	s_or_b64 exec, exec, s[10:11]
	s_waitcnt lgkmcnt(0)
	s_barrier
	v_cmp_gt_u32_e32 vcc, 0x100, v0
	s_and_saveexec_b64 s[98:99], vcc
	s_cbranch_execz .Lss_skip_op
	v_lshlrev_b32_e32 v172, 4, v0
	v_add_u32_e32 v172, 0x20400, v172
	ds_read_b128 v[176:179], v172
	s_lshl_b32 s10, s86, 8
	v_add_u32_e32 v170, s10, v0
	v_lshlrev_b32_e32 v170, 7, v170
	s_lshl_b32 s10, s8, 2
	v_add_u32_e32 v170, s10, v170
	v_mov_b32_e32 v171, 0
	v_lshl_add_u64 v[170:171], s[30:31], 0, v[170:171]
	s_waitcnt lgkmcnt(0)
	global_store_dwordx4 v[170:171], v[176:179], off
